# LN1 phases: per-column LayerNorm/modulation constants loaded once and kept in VGPRs (memoized after first rows), removing 7 serialized load round trips per row
# speedup vs baseline: 1.0059x; 1.0059x over previous
; DI int TID() { int t = threadIdx.x; asm volatile("" : "+v"(t)); return t; }
; DI const float* modp(const Params& p, int layer, int v) { return (const float*)(p.ws + OFF_MOD) + (size_t)(layer * 2 + v) * 12288; }
; __device__ __forceinline__ void phase_ln1(const Params& p, int layer, int row0) {
;   const int tid_ = TID(); const int lane = tid_ & 63, wid = tid_ >> 6;
;   const float* PRE = (const float*)(p.ws + OFF_P);
;   float* XR = (float*)(p.ws + OFF_XRES);
;   u16* XM = (u16*)(p.ws + OFF_XM);
;   const float* G = p.ln1_g + layer * DM;
;   const float* B = p.ln1_b + layer * DM;
;   for (int row = row0 + blockIdx.x * 4 + wid; row < TT; row += gridDim.x * 4) {
;     const float* md = modp(p, layer, row < NCTX ? 1 : 0);
;     float v[32];
;     float s = 0.f;
; #pragma unroll
;     for (int c = 0; c < 4; ++c) {
;       int col = c * 512 + lane * 8;
;       f32x4 a = *(const f32x4*)(PRE + (size_t)row * LDF + col), b = *(const f32x4*)(PRE + (size_t)row * LDF + col + 4);
; #pragma unroll
;       for (int e = 0; e < 4; ++e) { v[c * 8 + e] = a[e]; v[c * 8 + 4 + e] = b[e]; s += a[e] + b[e]; }
;     }
;     const float mu = wave_sum(s) * (1.f / 2048.f);
.LBB0_1811:
	s_or_b64 exec, exec, s[0:1]
	s_mov_b64 s[6:7], 0
	s_waitcnt lgkmcnt(0)
	v_mov_b32_e32 v0, v211
	s_barrier
	s_movk_i32 s2, 0x4100
	v_ashrrev_i32_e32 v1, 6, v0
	v_add_u32_e32 v62, s76, v1
	s_mov_b64 s[0:1], 0
	v_cmp_gt_i32_e32 vcc, s2, v62
	s_and_saveexec_b64 s[4:5], vcc
	s_cbranch_execz .LBB0_1814
	v_and_b32_e32 v1, 64, v214
	v_add_u32_e32 v1, 64, v1
	v_xor_b32_e32 v2, 32, v214
	v_cmp_lt_i32_e32 vcc, v2, v1
	s_add_u32 s8, s86, s6
	s_addc_u32 s9, s87, s7
	v_cndmask_b32_e32 v2, v214, v2, vcc
	v_lshlrev_b32_e32 v63, 2, v2
	v_xor_b32_e32 v2, 16, v214
	v_cmp_lt_i32_e32 vcc, v2, v1
	v_lshlrev_b32_e32 v0, 3, v0
	s_add_u32 s10, s8, 0xea70100
	v_cndmask_b32_e32 v2, v214, v2, vcc
	v_lshlrev_b32_e32 v64, 2, v2
	v_xor_b32_e32 v2, 8, v214
	v_cmp_lt_i32_e32 vcc, v2, v1
	v_and_b32_e32 v0, 0x1f8, v0
	s_addc_u32 s11, s9, 0
	v_cndmask_b32_e32 v2, v214, v2, vcc
	v_lshlrev_b32_e32 v65, 2, v2
	v_xor_b32_e32 v2, 4, v214
	v_cmp_lt_i32_e32 vcc, v2, v1
	v_mov_b32_e32 v17, 0
	v_or_b32_e32 v4, 0x400, v0
	v_cndmask_b32_e32 v2, v214, v2, vcc
	v_lshlrev_b32_e32 v66, 2, v2
	v_xor_b32_e32 v2, 2, v214
	v_cmp_lt_i32_e32 vcc, v2, v1
	v_lshlrev_b32_e32 v16, 2, v0
	s_add_u32 s12, s8, 0x1c1c0100
	v_cndmask_b32_e32 v2, v214, v2, vcc
	v_lshlrev_b32_e32 v67, 2, v2
	v_xor_b32_e32 v2, 1, v214
	v_cmp_lt_i32_e32 vcc, v2, v1
	v_lshl_add_u64 v[18:19], s[38:39], 0, v[16:17]
	v_lshl_add_u64 v[20:21], s[40:41], 0, v[16:17]
	v_cndmask_b32_e32 v1, v214, v2, vcc
	v_or_b32_e32 v2, 0x600, v0
	v_lshlrev_b32_e32 v16, 2, v4
	s_addc_u32 s13, s9, 0
	s_lshl_b32 s2, s74, 2
	v_lshl_add_u64 v[22:23], s[38:39], 0, v[16:17]
	v_lshl_add_u64 v[24:25], s[40:41], 0, v[16:17]
	v_lshlrev_b32_e32 v16, 2, v2
	v_lshl_add_u64 v[26:27], s[38:39], 0, v[16:17]
	v_lshl_add_u64 v[28:29], s[40:41], 0, v[16:17]
	s_add_u32 s6, s8, 0xa720000
	v_lshlrev_b32_e32 v16, 1, v0
	s_addc_u32 s7, s9, 0
	v_lshl_add_u64 v[6:7], s[8:9], 0, v[16:17]
	s_mov_b64 s[8:9], 0xa768100
	v_lshlrev_b32_e32 v68, 2, v1
	v_lshl_add_u64 v[30:31], v[6:7], 0, s[8:9]
	s_movk_i32 s3, 0x100
	v_mov_b32_e32 v69, 0xc000
	s_movk_i32 s16, 0x2080
	v_mov_b64_e32 v[32:33], s[10:11]
	v_lshlrev_b32_e32 v34, 2, v0
	v_mov_b32_e32 v35, v17
	v_lshlrev_b32_e32 v36, 2, v4
	v_mov_b32_e32 v37, v17
	v_lshlrev_b32_e32 v38, 2, v2
	v_mov_b32_e32 v39, v17
	v_mov_b64_e32 v[40:41], s[12:13]
	s_mov_b64 s[8:9], 0x8000
	s_mov_b64 s[10:11], 0x6000
	s_movk_i32 s17, 0x1080
	s_mov_b64 s[12:13], 0x8800
	s_mov_b64 s[14:15], 0x6800
	v_mov_b32_e32 v70, 0x3727c5ac
	s_mov_b32 s18, 0x800000
	s_mov_b32 s19, 0x8000
	s_movk_i32 s20, 0x6000
	s_movk_i32 s21, 0x40ff
	s_mov_b32 s98, 0
.LBB0_1813:
	v_mad_i64_i32 v[44:45], s[22:23], v62, s16, v[32:33]
	v_lshl_add_u64 v[56:57], v[44:45], 0, v[34:35]
	global_load_dwordx4 v[0:3], v[18:19], off offset:16
	global_load_dwordx4 v[4:7], v[18:19], off
	global_load_dwordx4 v[8:11], v[20:21], off offset:16
	global_load_dwordx4 v[12:15], v[20:21], off
	v_lshl_add_u64 v[58:59], v[44:45], 0, v[36:37]
	v_lshl_add_u64 v[60:61], v[44:45], 0, v[38:39]
	global_load_dwordx4 v[48:51], v[56:57], off offset:16
	global_load_dwordx4 v[52:55], v[56:57], off
	global_load_dwordx4 v[72:75], v[56:57], off offset:2064
	global_load_dwordx4 v[76:79], v[56:57], off offset:2048
	global_load_dwordx4 v[80:83], v[58:59], off offset:16
	global_load_dwordx4 v[84:87], v[58:59], off
	global_load_dwordx4 v[88:91], v[60:61], off offset:16
	global_load_dwordx4 v[92:95], v[60:61], off
	v_cmp_gt_i32_e32 vcc, s3, v62
	v_mad_i64_i32 v[42:43], s[22:23], v62, s16, v[40:41]
	s_nop 0
	v_cndmask_b32_e32 v16, 0, v69, vcc
	v_lshl_add_u64 v[44:45], s[6:7], 0, v[16:17]
	v_lshl_add_u64 v[56:57], v[44:45], 0, v[34:35]
	v_add_co_u32_e32 v96, vcc, s19, v56
	v_lshl_add_u64 v[46:47], v[42:43], 0, v[34:35]
	s_nop 0
	v_addc_co_u32_e32 v97, vcc, 0, v57, vcc
	v_add_co_u32_e32 v98, vcc, s20, v56
	v_lshl_add_u64 v[60:61], v[56:57], 0, s[8:9]
	s_nop 0
	v_addc_co_u32_e32 v99, vcc, 0, v57, vcc
	v_lshl_add_u64 v[58:59], v[56:57], 0, s[10:11]
	s_waitcnt vmcnt(6)
	v_mov_b32_e32 v136, v0
	v_mov_b32_e32 v137, v1
	v_mov_b32_e32 v138, v2
	v_mov_b32_e32 v139, v3
	v_mov_b32_e32 v140, v4
	v_mov_b32_e32 v141, v5
	v_mov_b32_e32 v142, v6
	v_mov_b32_e32 v143, v7
	v_mov_b32_e32 v144, v8
	v_mov_b32_e32 v145, v9
	v_mov_b32_e32 v146, v10
	v_mov_b32_e32 v147, v11
	v_mov_b32_e32 v148, v12
	v_mov_b32_e32 v149, v13
	v_mov_b32_e32 v150, v14
	v_mov_b32_e32 v151, v15
	v_add_f32_e32 v16, v52, v48
	v_add_f32_e32 v71, v53, v49
	v_add_f32_e32 v16, 0, v16
	v_add_f32_e32 v104, v54, v50
	v_add_f32_e32 v16, v71, v16
	v_add_f32_e32 v105, v55, v51
	v_add_f32_e32 v16, v104, v16
	s_waitcnt vmcnt(4)
	v_add_f32_e32 v106, v76, v72
	v_add_f32_e32 v16, v105, v16
	v_add_f32_e32 v107, v77, v73
	v_add_f32_e32 v16, v106, v16
	v_add_f32_e32 v108, v78, v74
	v_add_f32_e32 v16, v107, v16
	v_add_f32_e32 v109, v79, v75
	v_add_f32_e32 v16, v108, v16
	s_waitcnt vmcnt(2)
	v_add_f32_e32 v110, v84, v80
	v_add_f32_e32 v16, v109, v16
	v_add_f32_e32 v111, v85, v81
	v_add_f32_e32 v16, v110, v16
	v_add_f32_e32 v112, v86, v82
	v_add_f32_e32 v16, v111, v16
	v_add_f32_e32 v113, v87, v83
	v_add_f32_e32 v16, v112, v16
	s_waitcnt vmcnt(0)
	v_pk_add_f32 v[100:101], v[92:93], v[88:89]
	v_add_f32_e32 v16, v113, v16
	v_add_f32_e32 v16, v100, v16
	v_pk_add_f32 v[102:103], v[94:95], v[90:91]
	v_add_f32_e32 v16, v101, v16
	v_add_f32_e32 v16, v102, v16
	v_add_f32_e32 v16, v103, v16
	ds_bpermute_b32 v71, v63, v16
	s_waitcnt lgkmcnt(0)
	v_add_f32_e32 v16, v16, v71
	ds_bpermute_b32 v71, v64, v16
	s_waitcnt lgkmcnt(0)
	v_add_f32_e32 v16, v16, v71
	ds_bpermute_b32 v71, v65, v16
	s_waitcnt lgkmcnt(0)
	v_add_f32_e32 v16, v16, v71
	ds_bpermute_b32 v71, v66, v16
	s_waitcnt lgkmcnt(0)
; DI unsigned pk2(float a, float b) { f32x2 v = {a, b}; bf2_t r = __builtin_convertvector(v, bf2_t); return __builtin_bit_cast(unsigned, r); }
; __device__ __forceinline__ void phase_ln1(const Params& p, int layer, int row0) {
;     ...
;     const float mu = wave_sum(s) * (1.f / 2048.f);
;     float q = 0.f;
; #pragma unroll
;     for (int e = 0; e < 32; ++e) { float d = v[e] - mu; q += d * d; }
;     const float rstd = rsqrtf(wave_sum(q) * (1.f / 2048.f) + LN_EPS);
; #pragma unroll
;     for (int c = 0; c < 4; ++c) {
;       int col = c * 512 + lane * 8;
;       float y[8];
; #pragma unroll
;       for (int e = 0; e < 8; ++e) y[e] = (v[c * 8 + e] - mu) * rstd * G[col + e] + B[col + e];
;       *(f32x4*)(XR + (size_t)row * LDF + col) = f32x4{y[0], y[1], y[2], y[3]};
;       *(f32x4*)(XR + (size_t)row * LDF + col + 4) = f32x4{y[4], y[5], y[6], y[7]};
;       float z[8];
; #pragma unroll
;       for (int e = 0; e < 8; ++e) z[e] = y[e] * (1.f + md[8192 + col + e]) + md[6144 + col + e];
;       u32x4 o = {pk2(z[0], z[1]), pk2(z[2], z[3]), pk2(z[4], z[5]), pk2(z[6], z[7])};
;       *(u32x4*)(XM + (size_t)row * LDX + col) = o;
	v_add_f32_e32 v16, v16, v71
	ds_bpermute_b32 v71, v67, v16
	s_waitcnt lgkmcnt(0)
	v_add_f32_e32 v16, v16, v71
	ds_bpermute_b32 v71, v68, v16
	s_waitcnt lgkmcnt(0)
	v_add_f32_e32 v16, v16, v71
	v_mul_f32_e32 v16, 0x3a000000, v16
	v_pk_add_f32 v[104:105], v[52:53], v[16:17] op_sel_hi:[1,0] neg_lo:[0,1] neg_hi:[0,1]
	v_pk_add_f32 v[106:107], v[54:55], v[16:17] op_sel_hi:[1,0] neg_lo:[0,1] neg_hi:[0,1]
	v_pk_add_f32 v[112:113], v[76:77], v[16:17] op_sel_hi:[1,0] neg_lo:[0,1] neg_hi:[0,1]
	v_pk_mul_f32 v[76:77], v[104:105], v[104:105]
	v_pk_add_f32 v[100:101], v[48:49], v[16:17] op_sel_hi:[1,0] neg_lo:[0,1] neg_hi:[0,1]
	v_pk_add_f32 v[102:103], v[50:51], v[16:17] op_sel_hi:[1,0] neg_lo:[0,1] neg_hi:[0,1]
	v_pk_add_f32 v[108:109], v[72:73], v[16:17] op_sel_hi:[1,0] neg_lo:[0,1] neg_hi:[0,1]
	v_pk_add_f32 v[110:111], v[74:75], v[16:17] op_sel_hi:[1,0] neg_lo:[0,1] neg_hi:[0,1]
	v_pk_add_f32 v[114:115], v[78:79], v[16:17] op_sel_hi:[1,0] neg_lo:[0,1] neg_hi:[0,1]
	v_pk_add_f32 v[80:81], v[80:81], v[16:17] op_sel_hi:[1,0] neg_lo:[0,1] neg_hi:[0,1]
	v_pk_add_f32 v[82:83], v[82:83], v[16:17] op_sel_hi:[1,0] neg_lo:[0,1] neg_hi:[0,1]
	v_pk_add_f32 v[84:85], v[84:85], v[16:17] op_sel_hi:[1,0] neg_lo:[0,1] neg_hi:[0,1]
	v_pk_add_f32 v[86:87], v[86:87], v[16:17] op_sel_hi:[1,0] neg_lo:[0,1] neg_hi:[0,1]
	v_pk_add_f32 v[48:49], v[88:89], v[16:17] op_sel_hi:[1,0] neg_lo:[0,1] neg_hi:[0,1]
	v_pk_add_f32 v[50:51], v[90:91], v[16:17] op_sel_hi:[1,0] neg_lo:[0,1] neg_hi:[0,1]
	v_pk_add_f32 v[52:53], v[92:93], v[16:17] op_sel_hi:[1,0] neg_lo:[0,1] neg_hi:[0,1]
	v_pk_add_f32 v[54:55], v[94:95], v[16:17] op_sel_hi:[1,0] neg_lo:[0,1] neg_hi:[0,1]
	v_pk_mul_f32 v[78:79], v[106:107], v[106:107]
	v_add_f32_e32 v16, v76, v77
	v_add_f32_e32 v16, v78, v16
	v_pk_mul_f32 v[72:73], v[100:101], v[100:101]
	v_add_f32_e32 v16, v79, v16
	v_add_f32_e32 v16, v72, v16
	v_pk_mul_f32 v[74:75], v[102:103], v[102:103]
	v_add_f32_e32 v16, v73, v16
	v_add_f32_e32 v16, v74, v16
	v_pk_mul_f32 v[92:93], v[112:113], v[112:113]
	v_add_f32_e32 v16, v75, v16
	v_add_f32_e32 v16, v92, v16
	v_pk_mul_f32 v[94:95], v[114:115], v[114:115]
	v_add_f32_e32 v16, v93, v16
	v_add_f32_e32 v16, v94, v16
	v_pk_mul_f32 v[88:89], v[108:109], v[108:109]
	v_add_f32_e32 v16, v95, v16
	v_add_f32_e32 v16, v88, v16
	v_pk_mul_f32 v[90:91], v[110:111], v[110:111]
	v_add_f32_e32 v16, v89, v16
	v_add_f32_e32 v16, v90, v16
	v_pk_mul_f32 v[120:121], v[84:85], v[84:85]
	v_add_f32_e32 v16, v91, v16
	v_add_f32_e32 v16, v120, v16
	v_pk_mul_f32 v[122:123], v[86:87], v[86:87]
	v_add_f32_e32 v16, v121, v16
	v_add_f32_e32 v16, v122, v16
	v_pk_mul_f32 v[116:117], v[80:81], v[80:81]
	v_add_f32_e32 v16, v123, v16
	v_add_f32_e32 v16, v116, v16
	v_pk_mul_f32 v[118:119], v[82:83], v[82:83]
	v_add_f32_e32 v16, v117, v16
	v_add_f32_e32 v16, v118, v16
	v_pk_mul_f32 v[128:129], v[52:53], v[52:53]
	v_add_f32_e32 v16, v119, v16
	v_add_f32_e32 v16, v128, v16
	v_pk_mul_f32 v[130:131], v[54:55], v[54:55]
	v_add_f32_e32 v16, v129, v16
	v_add_f32_e32 v16, v130, v16
	v_pk_mul_f32 v[124:125], v[48:49], v[48:49]
	v_add_f32_e32 v16, v131, v16
	v_add_f32_e32 v16, v124, v16
	v_pk_mul_f32 v[126:127], v[50:51], v[50:51]
	v_add_f32_e32 v16, v125, v16
	v_add_f32_e32 v16, v126, v16
	v_add_f32_e32 v16, v127, v16
	ds_bpermute_b32 v71, v63, v16
	s_waitcnt lgkmcnt(0)
	v_add_f32_e32 v16, v16, v71
	ds_bpermute_b32 v71, v64, v16
	s_waitcnt lgkmcnt(0)
	v_add_f32_e32 v16, v16, v71
	ds_bpermute_b32 v71, v65, v16
	s_waitcnt lgkmcnt(0)
	v_add_f32_e32 v16, v16, v71
	ds_bpermute_b32 v71, v66, v16
	s_waitcnt lgkmcnt(0)
	v_add_f32_e32 v16, v16, v71
	ds_bpermute_b32 v71, v67, v16
	s_waitcnt lgkmcnt(0)
	v_add_f32_e32 v16, v16, v71
	ds_bpermute_b32 v71, v68, v16
	s_waitcnt lgkmcnt(0)
	v_add_f32_e32 v16, v16, v71
	v_fmamk_f32 v16, v16, 0x3a000000, v70
	v_mul_f32_e32 v71, 0x4b800000, v16
	v_cmp_gt_f32_e32 vcc, s18, v16
	s_nop 1
	v_cndmask_b32_e32 v16, v16, v71, vcc
	v_rsq_f32_e32 v16, v16
	s_nop 0
	v_mul_f32_e32 v71, 0x45800000, v16
	v_cndmask_b32_e32 v16, v16, v71, vcc
	v_pk_mul_f32 v[72:73], v[104:105], v[16:17] op_sel_hi:[1,0]
	v_pk_mul_f32 v[74:75], v[106:107], v[16:17] op_sel_hi:[1,0]
	v_pk_mul_f32 v[76:77], v[100:101], v[16:17] op_sel_hi:[1,0]
	v_pk_mul_f32 v[78:79], v[102:103], v[16:17] op_sel_hi:[1,0]
	v_pk_fma_f32 v[4:5], v[4:5], v[72:73], v[12:13]
	v_pk_fma_f32 v[6:7], v[6:7], v[74:75], v[14:15]
	v_pk_fma_f32 v[8:9], v[0:1], v[76:77], v[8:9]
	v_pk_fma_f32 v[10:11], v[2:3], v[78:79], v[10:11]
	global_store_dwordx4 v[46:47], v[4:7], off
	global_store_dwordx4 v[46:47], v[8:11], off offset:16
	global_load_dwordx4 v[12:15], v[96:97], off
	global_load_dwordx4 v[72:75], v[60:61], off offset:16
	global_load_dwordx4 v[76:79], v[98:99], off
	s_nop 0
	global_load_dwordx4 v[58:61], v[58:59], off offset:16
	v_mad_i64_i32 v[0:1], s[22:23], v62, s17, v[30:31]
	v_pk_mul_f32 v[80:81], v[80:81], v[16:17] op_sel_hi:[1,0]
	v_pk_mul_f32 v[82:83], v[82:83], v[16:17] op_sel_hi:[1,0]
	v_pk_mul_f32 v[48:49], v[48:49], v[16:17] op_sel_hi:[1,0]
	v_pk_mul_f32 v[50:51], v[50:51], v[16:17] op_sel_hi:[1,0]
	v_add_u32_e32 v62, s2, v62
	s_waitcnt vmcnt(3)
	v_mov_b32_e32 v152, v12
	v_mov_b32_e32 v153, v13
	v_mov_b32_e32 v154, v14
	v_mov_b32_e32 v155, v15
	v_pk_add_f32 v[2:3], v[12:13], 1.0 op_sel_hi:[1,0]
	v_pk_add_f32 v[12:13], v[14:15], 1.0 op_sel_hi:[1,0]
	s_waitcnt vmcnt(2)
	v_mov_b32_e32 v156, v72
	v_mov_b32_e32 v157, v73
	v_mov_b32_e32 v158, v74
	v_mov_b32_e32 v159, v75
	v_pk_add_f32 v[14:15], v[72:73], 1.0 op_sel_hi:[1,0]
	v_pk_add_f32 v[72:73], v[74:75], 1.0 op_sel_hi:[1,0]
	s_waitcnt vmcnt(1)
; DI unsigned pk2(float a, float b) { f32x2 v = {a, b}; bf2_t r = __builtin_convertvector(v, bf2_t); return __builtin_bit_cast(unsigned, r); }
; __device__ __forceinline__ void phase_ln1(const Params& p, int layer, int row0) {
;     ...
; #pragma unroll
;     for (int c = 0; c < 4; ++c) {
;       int col = c * 512 + lane * 8;
;       float y[8];
; #pragma unroll
;       for (int e = 0; e < 8; ++e) y[e] = (v[c * 8 + e] - mu) * rstd * G[col + e] + B[col + e];
;       *(f32x4*)(XR + (size_t)row * LDF + col) = f32x4{y[0], y[1], y[2], y[3]};
;       *(f32x4*)(XR + (size_t)row * LDF + col + 4) = f32x4{y[4], y[5], y[6], y[7]};
;       float z[8];
; #pragma unroll
;       for (int e = 0; e < 8; ++e) z[e] = y[e] * (1.f + md[8192 + col + e]) + md[6144 + col + e];
;       u32x4 o = {pk2(z[0], z[1]), pk2(z[2], z[3]), pk2(z[4], z[5]), pk2(z[6], z[7])};
;       *(u32x4*)(XM + (size_t)row * LDX + col) = o;
	v_mov_b32_e32 v160, v76
	v_mov_b32_e32 v161, v77
	v_mov_b32_e32 v162, v78
	v_mov_b32_e32 v163, v79
	v_pk_fma_f32 v[2:3], v[2:3], v[4:5], v[76:77]
	v_pk_fma_f32 v[4:5], v[12:13], v[6:7], v[78:79]
	s_waitcnt vmcnt(0)
	v_mov_b32_e32 v164, v58
	v_mov_b32_e32 v165, v59
	v_mov_b32_e32 v166, v60
	v_mov_b32_e32 v167, v61
	v_pk_fma_f32 v[6:7], v[14:15], v[8:9], v[58:59]
	v_pk_fma_f32 v[8:9], v[72:73], v[10:11], v[60:61]
	v_cvt_pk_bf16_f32 v2, v2, v3
	v_cvt_pk_bf16_f32 v3, v4, v5
	v_cvt_pk_bf16_f32 v4, v6, v7
	v_cvt_pk_bf16_f32 v5, v8, v9
	global_store_dwordx4 v[0:1], v[2:5], off
	global_load_dwordx4 v[2:5], v[20:21], off offset:2048
	s_nop 0
	global_load_dwordx4 v[6:9], v[18:19], off offset:2048
	global_load_dwordx4 v[10:13], v[18:19], off offset:2064
	global_load_dwordx4 v[58:61], v[20:21], off offset:2064
	v_lshl_add_u64 v[14:15], v[56:57], 0, s[12:13]
	v_lshl_add_u64 v[76:77], v[56:57], 0, s[14:15]
	v_pk_mul_f32 v[56:57], v[112:113], v[16:17] op_sel_hi:[1,0]
	v_pk_mul_f32 v[72:73], v[114:115], v[16:17] op_sel_hi:[1,0]
	v_pk_mul_f32 v[74:75], v[108:109], v[16:17] op_sel_hi:[1,0]
	v_pk_mul_f32 v[78:79], v[110:111], v[16:17] op_sel_hi:[1,0]
	s_waitcnt vmcnt(2)
	v_mov_b32_e32 v168, v2
	v_mov_b32_e32 v169, v3
	v_mov_b32_e32 v170, v4
	v_mov_b32_e32 v171, v5
	v_mov_b32_e32 v172, v6
	v_mov_b32_e32 v173, v7
	v_mov_b32_e32 v174, v8
	v_mov_b32_e32 v175, v9
	v_pk_fma_f32 v[2:3], v[6:7], v[56:57], v[2:3]
	v_pk_fma_f32 v[4:5], v[8:9], v[72:73], v[4:5]
	s_waitcnt vmcnt(0)
	v_mov_b32_e32 v176, v10
	v_mov_b32_e32 v177, v11
	v_mov_b32_e32 v178, v12
	v_mov_b32_e32 v179, v13
	v_mov_b32_e32 v180, v58
	v_mov_b32_e32 v181, v59
	v_mov_b32_e32 v182, v60
	v_mov_b32_e32 v183, v61
	v_pk_fma_f32 v[6:7], v[10:11], v[74:75], v[58:59]
	v_pk_fma_f32 v[8:9], v[12:13], v[78:79], v[60:61]
	global_store_dwordx4 v[46:47], v[2:5], off offset:2048
	global_store_dwordx4 v[46:47], v[6:9], off offset:2064
	global_load_dwordx4 v[10:13], v[96:97], off offset:2048
	global_load_dwordx4 v[56:59], v[14:15], off offset:16
	global_load_dwordx4 v[72:75], v[98:99], off offset:2048
	s_nop 0
	global_load_dwordx4 v[76:79], v[76:77], off offset:16
	s_waitcnt vmcnt(3)
	v_mov_b32_e32 v184, v10
	v_mov_b32_e32 v185, v11
	v_mov_b32_e32 v186, v12
	v_mov_b32_e32 v187, v13
	v_pk_add_f32 v[10:11], v[10:11], 1.0 op_sel_hi:[1,0]
	v_pk_add_f32 v[12:13], v[12:13], 1.0 op_sel_hi:[1,0]
	s_waitcnt vmcnt(2)
	v_mov_b32_e32 v188, v56
	v_mov_b32_e32 v189, v57
	v_mov_b32_e32 v190, v58
	v_mov_b32_e32 v191, v59
	v_pk_add_f32 v[14:15], v[56:57], 1.0 op_sel_hi:[1,0]
	v_pk_add_f32 v[46:47], v[58:59], 1.0 op_sel_hi:[1,0]
	s_waitcnt vmcnt(1)
	v_mov_b32_e32 v192, v72
	v_mov_b32_e32 v193, v73
	v_mov_b32_e32 v194, v74
	v_mov_b32_e32 v195, v75
	v_pk_fma_f32 v[2:3], v[10:11], v[2:3], v[72:73]
	v_pk_fma_f32 v[4:5], v[4:5], v[12:13], v[74:75]
	s_waitcnt vmcnt(0)
	v_mov_b32_e32 v196, v76
	v_mov_b32_e32 v197, v77
	v_mov_b32_e32 v198, v78
	v_mov_b32_e32 v199, v79
	v_pk_fma_f32 v[6:7], v[6:7], v[14:15], v[76:77]
	v_pk_fma_f32 v[8:9], v[8:9], v[46:47], v[78:79]
	v_cvt_pk_bf16_f32 v2, v2, v3
	v_cvt_pk_bf16_f32 v3, v4, v5
	v_cvt_pk_bf16_f32 v4, v6, v7
	v_cvt_pk_bf16_f32 v5, v8, v9
	global_store_dwordx4 v[0:1], v[2:5], off offset:1024
	global_load_dwordx4 v[2:5], v[24:25], off
	s_nop 0
	global_load_dwordx4 v[6:9], v[22:23], off
	global_load_dwordx4 v[10:13], v[22:23], off offset:16
	global_load_dwordx4 v[56:59], v[24:25], off offset:16
	v_lshl_add_u64 v[46:47], v[44:45], 0, v[36:37]
	v_add_co_u32_e32 v72, vcc, s19, v46
	v_pk_mul_f32 v[74:75], v[84:85], v[16:17] op_sel_hi:[1,0]
	v_pk_mul_f32 v[78:79], v[86:87], v[16:17] op_sel_hi:[1,0]
	v_lshl_add_u64 v[14:15], v[42:43], 0, v[36:37]
	v_addc_co_u32_e32 v73, vcc, 0, v47, vcc
	v_lshl_add_u64 v[60:61], v[46:47], 0, s[8:9]
	v_lshl_add_u64 v[76:77], v[46:47], 0, s[10:11]
	v_add_co_u32_e32 v46, vcc, s20, v46
	s_waitcnt vmcnt(2)
	v_mov_b32_e32 v200, v2
	v_mov_b32_e32 v201, v3
	v_mov_b32_e32 v202, v4
	v_mov_b32_e32 v203, v5
	v_mov_b32_e32 v204, v6
	v_mov_b32_e32 v205, v7
	v_mov_b32_e32 v206, v8
	v_mov_b32_e32 v207, v9
	v_pk_fma_f32 v[2:3], v[74:75], v[6:7], v[2:3]
	v_pk_fma_f32 v[4:5], v[78:79], v[8:9], v[4:5]
	s_waitcnt vmcnt(0)
	v_mov_b32_e32 v208, v10
	v_mov_b32_e32 v209, v11
	v_mov_b32_e32 v210, v12
	v_mov_b32_e32 v212, v13
	v_mov_b32_e32 v213, v56
	v_mov_b32_e32 v215, v57
	v_mov_b32_e32 v216, v58
	v_mov_b32_e32 v217, v59
	v_pk_fma_f32 v[6:7], v[80:81], v[10:11], v[56:57]
	v_pk_fma_f32 v[8:9], v[82:83], v[12:13], v[58:59]
	global_store_dwordx4 v[14:15], v[2:5], off
	global_store_dwordx4 v[14:15], v[6:9], off offset:16
	v_addc_co_u32_e32 v47, vcc, 0, v47, vcc
	global_load_dwordx4 v[10:13], v[72:73], off
	global_load_dwordx4 v[56:59], v[60:61], off offset:16
	s_nop 0
	global_load_dwordx4 v[72:75], v[46:47], off
	s_nop 0
	global_load_dwordx4 v[76:79], v[76:77], off offset:16
	s_waitcnt vmcnt(3)
	v_mov_b32_e32 v218, v10
	v_mov_b32_e32 v219, v11
	v_mov_b32_e32 v220, v12
	v_mov_b32_e32 v221, v13
	v_pk_add_f32 v[10:11], v[10:11], 1.0 op_sel_hi:[1,0]
	v_pk_add_f32 v[12:13], v[12:13], 1.0 op_sel_hi:[1,0]
	s_waitcnt vmcnt(2)
	v_mov_b32_e32 v222, v56
	v_mov_b32_e32 v223, v57
	v_mov_b32_e32 v224, v58
	v_mov_b32_e32 v225, v59
	v_pk_add_f32 v[14:15], v[56:57], 1.0 op_sel_hi:[1,0]
	v_pk_add_f32 v[46:47], v[58:59], 1.0 op_sel_hi:[1,0]
	s_waitcnt vmcnt(1)
	v_mov_b32_e32 v226, v72
	v_mov_b32_e32 v227, v73
	v_mov_b32_e32 v228, v74
	v_mov_b32_e32 v229, v75
	v_pk_fma_f32 v[2:3], v[2:3], v[10:11], v[72:73]
	v_pk_fma_f32 v[4:5], v[4:5], v[12:13], v[74:75]
	s_waitcnt vmcnt(0)
; DI unsigned pk2(float a, float b) { f32x2 v = {a, b}; bf2_t r = __builtin_convertvector(v, bf2_t); return __builtin_bit_cast(unsigned, r); }
; __device__ __forceinline__ void phase_ln1(const Params& p, int layer, int row0) {
;     ...
; #pragma unroll
;     for (int c = 0; c < 4; ++c) {
;       int col = c * 512 + lane * 8;
;       float y[8];
; #pragma unroll
;       for (int e = 0; e < 8; ++e) y[e] = (v[c * 8 + e] - mu) * rstd * G[col + e] + B[col + e];
;       *(f32x4*)(XR + (size_t)row * LDF + col) = f32x4{y[0], y[1], y[2], y[3]};
;       *(f32x4*)(XR + (size_t)row * LDF + col + 4) = f32x4{y[4], y[5], y[6], y[7]};
;       float z[8];
; #pragma unroll
;       for (int e = 0; e < 8; ++e) z[e] = y[e] * (1.f + md[8192 + col + e]) + md[6144 + col + e];
;       u32x4 o = {pk2(z[0], z[1]), pk2(z[2], z[3]), pk2(z[4], z[5]), pk2(z[6], z[7])};
;       *(u32x4*)(XM + (size_t)row * LDX + col) = o;
;     }
	v_mov_b32_e32 v230, v76
	v_mov_b32_e32 v231, v77
	v_mov_b32_e32 v232, v78
	v_mov_b32_e32 v233, v79
	v_pk_fma_f32 v[6:7], v[6:7], v[14:15], v[76:77]
	v_pk_fma_f32 v[8:9], v[8:9], v[46:47], v[78:79]
	v_cvt_pk_bf16_f32 v2, v2, v3
	v_cvt_pk_bf16_f32 v3, v4, v5
	v_cvt_pk_bf16_f32 v4, v6, v7
	v_cvt_pk_bf16_f32 v5, v8, v9
	global_store_dwordx4 v[0:1], v[2:5], off offset:2048
	global_load_dwordx4 v[2:5], v[28:29], off
	s_nop 0
	global_load_dwordx4 v[6:9], v[26:27], off
	global_load_dwordx4 v[10:13], v[26:27], off offset:16
	global_load_dwordx4 v[56:59], v[28:29], off offset:16
	v_lshl_add_u64 v[14:15], v[42:43], 0, v[38:39]
	v_lshl_add_u64 v[42:43], v[44:45], 0, v[38:39]
	v_add_co_u32_e32 v46, vcc, s19, v42
	v_lshl_add_u64 v[44:45], v[42:43], 0, s[8:9]
	s_nop 0
	v_addc_co_u32_e32 v47, vcc, 0, v43, vcc
	v_add_co_u32_e32 v72, vcc, s20, v42
	v_lshl_add_u64 v[60:61], v[42:43], 0, s[10:11]
	s_nop 0
	v_addc_co_u32_e32 v73, vcc, 0, v43, vcc
	v_pk_mul_f32 v[42:43], v[52:53], v[16:17] op_sel_hi:[1,0]
	v_pk_mul_f32 v[52:53], v[54:55], v[16:17] op_sel_hi:[1,0]
	v_cmp_lt_i32_e32 vcc, s21, v62
	s_or_b64 s[0:1], vcc, s[0:1]
	s_waitcnt vmcnt(2)
	v_mov_b32_e32 v234, v2
	v_mov_b32_e32 v235, v3
	v_mov_b32_e32 v236, v4
	v_mov_b32_e32 v237, v5
	v_mov_b32_e32 v238, v6
	v_mov_b32_e32 v240, v7
	v_mov_b32_e32 v241, v8
	v_mov_b32_e32 v242, v9
	v_pk_fma_f32 v[2:3], v[42:43], v[6:7], v[2:3]
	v_pk_fma_f32 v[4:5], v[52:53], v[8:9], v[4:5]
	s_waitcnt vmcnt(0)
	v_mov_b32_e32 v243, v10
	v_mov_b32_e32 v244, v11
	v_mov_b32_e32 v245, v12
	v_mov_b32_e32 v246, v13
	v_mov_b32_e32 v247, v56
	v_mov_b32_e32 v248, v57
	v_mov_b32_e32 v249, v58
	v_mov_b32_e32 v250, v59
	v_pk_fma_f32 v[6:7], v[48:49], v[10:11], v[56:57]
	v_pk_fma_f32 v[8:9], v[50:51], v[12:13], v[58:59]
	global_store_dwordx4 v[14:15], v[2:5], off
	global_store_dwordx4 v[14:15], v[6:9], off offset:16
	global_load_dwordx4 v[10:13], v[46:47], off
	s_nop 0
	global_load_dwordx4 v[42:45], v[44:45], off offset:16
	s_nop 0
	global_load_dwordx4 v[46:49], v[72:73], off
	global_load_dwordx4 v[50:53], v[60:61], off offset:16
	s_waitcnt vmcnt(3)
	v_pk_add_f32 v[10:11], v[10:11], 1.0 op_sel_hi:[1,0]
	v_pk_add_f32 v[12:13], v[12:13], 1.0 op_sel_hi:[1,0]
	s_waitcnt vmcnt(2)
	v_pk_add_f32 v[14:15], v[42:43], 1.0 op_sel_hi:[1,0]
	v_pk_add_f32 v[42:43], v[44:45], 1.0 op_sel_hi:[1,0]
	s_waitcnt vmcnt(1)
	v_pk_fma_f32 v[2:3], v[2:3], v[10:11], v[46:47]
	v_pk_fma_f32 v[4:5], v[4:5], v[12:13], v[48:49]
	s_waitcnt vmcnt(0)
	v_pk_fma_f32 v[6:7], v[6:7], v[14:15], v[50:51]
	v_pk_fma_f32 v[8:9], v[8:9], v[42:43], v[52:53]
	v_cvt_pk_bf16_f32 v2, v2, v3
	v_cvt_pk_bf16_f32 v3, v4, v5
	v_cvt_pk_bf16_f32 v4, v6, v7
	v_cvt_pk_bf16_f32 v5, v8, v9
	global_store_dwordx4 v[0:1], v[2:5], off offset:3072
	s_andn2_b64 exec, exec, s[0:1]
	s_cbranch_execz .LBB0_1814
	s_add_u32 s98, s98, 1
	s_cmp_lt_u32 s98, 2
	s_cbranch_scc1 .LBB0_1813
.Lln1_B0:
	v_mad_i64_i32 v[44:45], s[22:23], v62, s16, v[32:33]
	v_lshl_add_u64 v[56:57], v[44:45], 0, v[34:35]
	v_lshl_add_u64 v[58:59], v[44:45], 0, v[36:37]
	v_lshl_add_u64 v[60:61], v[44:45], 0, v[38:39]
	global_load_dwordx4 v[48:51], v[56:57], off offset:16
	global_load_dwordx4 v[52:55], v[56:57], off
	global_load_dwordx4 v[72:75], v[56:57], off offset:2064
	global_load_dwordx4 v[76:79], v[56:57], off offset:2048
	global_load_dwordx4 v[80:83], v[58:59], off offset:16
	global_load_dwordx4 v[84:87], v[58:59], off
	global_load_dwordx4 v[88:91], v[60:61], off offset:16
	global_load_dwordx4 v[92:95], v[60:61], off
	v_cmp_gt_i32_e32 vcc, s3, v62
	v_mad_i64_i32 v[42:43], s[22:23], v62, s16, v[40:41]
	s_nop 0
	v_cndmask_b32_e32 v16, 0, v69, vcc
	v_lshl_add_u64 v[44:45], s[6:7], 0, v[16:17]
	v_lshl_add_u64 v[56:57], v[44:45], 0, v[34:35]
	v_add_co_u32_e32 v96, vcc, s19, v56
	v_lshl_add_u64 v[46:47], v[42:43], 0, v[34:35]
	s_nop 0
	v_addc_co_u32_e32 v97, vcc, 0, v57, vcc
	v_add_co_u32_e32 v98, vcc, s20, v56
	v_lshl_add_u64 v[60:61], v[56:57], 0, s[8:9]
	s_nop 0
	v_addc_co_u32_e32 v99, vcc, 0, v57, vcc
	v_lshl_add_u64 v[58:59], v[56:57], 0, s[10:11]
	s_waitcnt vmcnt(6)
	s_nop 1
	v_mov_b32_e32 v0, v136
	v_mov_b32_e32 v1, v137
	v_mov_b32_e32 v2, v138
	v_mov_b32_e32 v3, v139
	v_mov_b32_e32 v4, v140
	v_mov_b32_e32 v5, v141
	v_mov_b32_e32 v6, v142
	v_mov_b32_e32 v7, v143
	v_mov_b32_e32 v8, v144
	v_mov_b32_e32 v9, v145
	v_mov_b32_e32 v10, v146
	v_mov_b32_e32 v11, v147
	v_mov_b32_e32 v12, v148
	v_mov_b32_e32 v13, v149
	v_mov_b32_e32 v14, v150
	v_mov_b32_e32 v15, v151
	v_add_f32_e32 v16, v52, v48
	v_add_f32_e32 v71, v53, v49
	v_add_f32_e32 v16, 0, v16
	v_add_f32_e32 v104, v54, v50
	v_add_f32_e32 v16, v71, v16
	v_add_f32_e32 v105, v55, v51
	v_add_f32_e32 v16, v104, v16
	s_waitcnt vmcnt(4)
	v_add_f32_e32 v106, v76, v72
	v_add_f32_e32 v16, v105, v16
	v_add_f32_e32 v107, v77, v73
	v_add_f32_e32 v16, v106, v16
	v_add_f32_e32 v108, v78, v74
	v_add_f32_e32 v16, v107, v16
	v_add_f32_e32 v109, v79, v75
	v_add_f32_e32 v16, v108, v16
	s_waitcnt vmcnt(2)
	v_add_f32_e32 v110, v84, v80
	v_add_f32_e32 v16, v109, v16
	v_add_f32_e32 v111, v85, v81
	v_add_f32_e32 v16, v110, v16
	v_add_f32_e32 v112, v86, v82
	v_add_f32_e32 v16, v111, v16
	v_add_f32_e32 v113, v87, v83
	v_add_f32_e32 v16, v112, v16
	s_waitcnt vmcnt(0)
	v_pk_add_f32 v[100:101], v[92:93], v[88:89]
	v_add_f32_e32 v16, v113, v16
	v_add_f32_e32 v16, v100, v16
	v_pk_add_f32 v[102:103], v[94:95], v[90:91]
	v_add_f32_e32 v16, v101, v16
	v_add_f32_e32 v16, v102, v16
	v_add_f32_e32 v16, v103, v16
	ds_bpermute_b32 v71, v63, v16
	s_waitcnt lgkmcnt(0)
	v_add_f32_e32 v16, v16, v71
	ds_bpermute_b32 v71, v64, v16
	s_waitcnt lgkmcnt(0)
	v_add_f32_e32 v16, v16, v71
	ds_bpermute_b32 v71, v65, v16
	s_waitcnt lgkmcnt(0)
; DI unsigned pk2(float a, float b) { f32x2 v = {a, b}; bf2_t r = __builtin_convertvector(v, bf2_t); return __builtin_bit_cast(unsigned, r); }
; __device__ __forceinline__ void phase_ln1(const Params& p, int layer, int row0) {
;     ...
;     const float mu = wave_sum(s) * (1.f / 2048.f);
;     float q = 0.f;
; #pragma unroll
;     for (int e = 0; e < 32; ++e) { float d = v[e] - mu; q += d * d; }
;     const float rstd = rsqrtf(wave_sum(q) * (1.f / 2048.f) + LN_EPS);
; #pragma unroll
;     for (int c = 0; c < 4; ++c) {
;       int col = c * 512 + lane * 8;
;       float y[8];
; #pragma unroll
;       for (int e = 0; e < 8; ++e) y[e] = (v[c * 8 + e] - mu) * rstd * G[col + e] + B[col + e];
;       *(f32x4*)(XR + (size_t)row * LDF + col) = f32x4{y[0], y[1], y[2], y[3]};
;       *(f32x4*)(XR + (size_t)row * LDF + col + 4) = f32x4{y[4], y[5], y[6], y[7]};
;       float z[8];
; #pragma unroll
;       for (int e = 0; e < 8; ++e) z[e] = y[e] * (1.f + md[8192 + col + e]) + md[6144 + col + e];
;       u32x4 o = {pk2(z[0], z[1]), pk2(z[2], z[3]), pk2(z[4], z[5]), pk2(z[6], z[7])};
;       *(u32x4*)(XM + (size_t)row * LDX + col) = o;
	v_add_f32_e32 v16, v16, v71
	ds_bpermute_b32 v71, v66, v16
	s_waitcnt lgkmcnt(0)
	v_add_f32_e32 v16, v16, v71
	ds_bpermute_b32 v71, v67, v16
	s_waitcnt lgkmcnt(0)
	v_add_f32_e32 v16, v16, v71
	ds_bpermute_b32 v71, v68, v16
	s_waitcnt lgkmcnt(0)
	v_add_f32_e32 v16, v16, v71
	v_mul_f32_e32 v16, 0x3a000000, v16
	v_pk_add_f32 v[104:105], v[52:53], v[16:17] op_sel_hi:[1,0] neg_lo:[0,1] neg_hi:[0,1]
	v_pk_add_f32 v[106:107], v[54:55], v[16:17] op_sel_hi:[1,0] neg_lo:[0,1] neg_hi:[0,1]
	v_pk_add_f32 v[112:113], v[76:77], v[16:17] op_sel_hi:[1,0] neg_lo:[0,1] neg_hi:[0,1]
	v_pk_mul_f32 v[76:77], v[104:105], v[104:105]
	v_pk_add_f32 v[100:101], v[48:49], v[16:17] op_sel_hi:[1,0] neg_lo:[0,1] neg_hi:[0,1]
	v_pk_add_f32 v[102:103], v[50:51], v[16:17] op_sel_hi:[1,0] neg_lo:[0,1] neg_hi:[0,1]
	v_pk_add_f32 v[108:109], v[72:73], v[16:17] op_sel_hi:[1,0] neg_lo:[0,1] neg_hi:[0,1]
	v_pk_add_f32 v[110:111], v[74:75], v[16:17] op_sel_hi:[1,0] neg_lo:[0,1] neg_hi:[0,1]
	v_pk_add_f32 v[114:115], v[78:79], v[16:17] op_sel_hi:[1,0] neg_lo:[0,1] neg_hi:[0,1]
	v_pk_add_f32 v[80:81], v[80:81], v[16:17] op_sel_hi:[1,0] neg_lo:[0,1] neg_hi:[0,1]
	v_pk_add_f32 v[82:83], v[82:83], v[16:17] op_sel_hi:[1,0] neg_lo:[0,1] neg_hi:[0,1]
	v_pk_add_f32 v[84:85], v[84:85], v[16:17] op_sel_hi:[1,0] neg_lo:[0,1] neg_hi:[0,1]
	v_pk_add_f32 v[86:87], v[86:87], v[16:17] op_sel_hi:[1,0] neg_lo:[0,1] neg_hi:[0,1]
	v_pk_add_f32 v[48:49], v[88:89], v[16:17] op_sel_hi:[1,0] neg_lo:[0,1] neg_hi:[0,1]
	v_pk_add_f32 v[50:51], v[90:91], v[16:17] op_sel_hi:[1,0] neg_lo:[0,1] neg_hi:[0,1]
	v_pk_add_f32 v[52:53], v[92:93], v[16:17] op_sel_hi:[1,0] neg_lo:[0,1] neg_hi:[0,1]
	v_pk_add_f32 v[54:55], v[94:95], v[16:17] op_sel_hi:[1,0] neg_lo:[0,1] neg_hi:[0,1]
	v_pk_mul_f32 v[78:79], v[106:107], v[106:107]
	v_add_f32_e32 v16, v76, v77
	v_add_f32_e32 v16, v78, v16
	v_pk_mul_f32 v[72:73], v[100:101], v[100:101]
	v_add_f32_e32 v16, v79, v16
	v_add_f32_e32 v16, v72, v16
	v_pk_mul_f32 v[74:75], v[102:103], v[102:103]
	v_add_f32_e32 v16, v73, v16
	v_add_f32_e32 v16, v74, v16
	v_pk_mul_f32 v[92:93], v[112:113], v[112:113]
	v_add_f32_e32 v16, v75, v16
	v_add_f32_e32 v16, v92, v16
	v_pk_mul_f32 v[94:95], v[114:115], v[114:115]
	v_add_f32_e32 v16, v93, v16
	v_add_f32_e32 v16, v94, v16
	v_pk_mul_f32 v[88:89], v[108:109], v[108:109]
	v_add_f32_e32 v16, v95, v16
	v_add_f32_e32 v16, v88, v16
	v_pk_mul_f32 v[90:91], v[110:111], v[110:111]
	v_add_f32_e32 v16, v89, v16
	v_add_f32_e32 v16, v90, v16
	v_pk_mul_f32 v[120:121], v[84:85], v[84:85]
	v_add_f32_e32 v16, v91, v16
	v_add_f32_e32 v16, v120, v16
	v_pk_mul_f32 v[122:123], v[86:87], v[86:87]
	v_add_f32_e32 v16, v121, v16
	v_add_f32_e32 v16, v122, v16
	v_pk_mul_f32 v[116:117], v[80:81], v[80:81]
	v_add_f32_e32 v16, v123, v16
	v_add_f32_e32 v16, v116, v16
	v_pk_mul_f32 v[118:119], v[82:83], v[82:83]
	v_add_f32_e32 v16, v117, v16
	v_add_f32_e32 v16, v118, v16
	v_pk_mul_f32 v[128:129], v[52:53], v[52:53]
	v_add_f32_e32 v16, v119, v16
	v_add_f32_e32 v16, v128, v16
	v_pk_mul_f32 v[130:131], v[54:55], v[54:55]
	v_add_f32_e32 v16, v129, v16
	v_add_f32_e32 v16, v130, v16
	v_pk_mul_f32 v[124:125], v[48:49], v[48:49]
	v_add_f32_e32 v16, v131, v16
	v_add_f32_e32 v16, v124, v16
	v_pk_mul_f32 v[126:127], v[50:51], v[50:51]
	v_add_f32_e32 v16, v125, v16
	v_add_f32_e32 v16, v126, v16
	v_add_f32_e32 v16, v127, v16
	ds_bpermute_b32 v71, v63, v16
	s_waitcnt lgkmcnt(0)
	v_add_f32_e32 v16, v16, v71
	ds_bpermute_b32 v71, v64, v16
	s_waitcnt lgkmcnt(0)
	v_add_f32_e32 v16, v16, v71
	ds_bpermute_b32 v71, v65, v16
	s_waitcnt lgkmcnt(0)
	v_add_f32_e32 v16, v16, v71
	ds_bpermute_b32 v71, v66, v16
	s_waitcnt lgkmcnt(0)
	v_add_f32_e32 v16, v16, v71
	ds_bpermute_b32 v71, v67, v16
	s_waitcnt lgkmcnt(0)
	v_add_f32_e32 v16, v16, v71
	ds_bpermute_b32 v71, v68, v16
	s_waitcnt lgkmcnt(0)
	v_add_f32_e32 v16, v16, v71
	v_fmamk_f32 v16, v16, 0x3a000000, v70
	v_mul_f32_e32 v71, 0x4b800000, v16
	v_cmp_gt_f32_e32 vcc, s18, v16
	s_nop 1
	v_cndmask_b32_e32 v16, v16, v71, vcc
	v_rsq_f32_e32 v16, v16
	s_nop 0
	v_mul_f32_e32 v71, 0x45800000, v16
	v_cndmask_b32_e32 v16, v16, v71, vcc
	v_pk_mul_f32 v[72:73], v[104:105], v[16:17] op_sel_hi:[1,0]
	v_pk_mul_f32 v[74:75], v[106:107], v[16:17] op_sel_hi:[1,0]
	v_pk_mul_f32 v[76:77], v[100:101], v[16:17] op_sel_hi:[1,0]
	v_pk_mul_f32 v[78:79], v[102:103], v[16:17] op_sel_hi:[1,0]
	v_pk_fma_f32 v[4:5], v[4:5], v[72:73], v[12:13]
	v_pk_fma_f32 v[6:7], v[6:7], v[74:75], v[14:15]
	v_pk_fma_f32 v[8:9], v[0:1], v[76:77], v[8:9]
	v_pk_fma_f32 v[10:11], v[2:3], v[78:79], v[10:11]
	global_store_dwordx4 v[46:47], v[4:7], off
	global_store_dwordx4 v[46:47], v[8:11], off offset:16
	s_nop 0
	v_mad_i64_i32 v[0:1], s[22:23], v62, s17, v[30:31]
	v_pk_mul_f32 v[80:81], v[80:81], v[16:17] op_sel_hi:[1,0]
	v_pk_mul_f32 v[82:83], v[82:83], v[16:17] op_sel_hi:[1,0]
	v_pk_mul_f32 v[48:49], v[48:49], v[16:17] op_sel_hi:[1,0]
	v_pk_mul_f32 v[50:51], v[50:51], v[16:17] op_sel_hi:[1,0]
	v_add_u32_e32 v62, s2, v62
	s_nop 1
	v_mov_b32_e32 v12, v152
	v_mov_b32_e32 v13, v153
	v_mov_b32_e32 v14, v154
	v_mov_b32_e32 v15, v155
	v_pk_add_f32 v[2:3], v[12:13], 1.0 op_sel_hi:[1,0]
	v_pk_add_f32 v[12:13], v[14:15], 1.0 op_sel_hi:[1,0]
	s_nop 1
	v_mov_b32_e32 v72, v156
	v_mov_b32_e32 v73, v157
	v_mov_b32_e32 v74, v158
	v_mov_b32_e32 v75, v159
	v_pk_add_f32 v[14:15], v[72:73], 1.0 op_sel_hi:[1,0]
	v_pk_add_f32 v[72:73], v[74:75], 1.0 op_sel_hi:[1,0]
	s_nop 1
	v_mov_b32_e32 v76, v160
	v_mov_b32_e32 v77, v161
	v_mov_b32_e32 v78, v162
	v_mov_b32_e32 v79, v163
	v_pk_fma_f32 v[2:3], v[2:3], v[4:5], v[76:77]
	v_pk_fma_f32 v[4:5], v[12:13], v[6:7], v[78:79]
	s_nop 1
	v_mov_b32_e32 v58, v164
	v_mov_b32_e32 v59, v165
; DI unsigned pk2(float a, float b) { f32x2 v = {a, b}; bf2_t r = __builtin_convertvector(v, bf2_t); return __builtin_bit_cast(unsigned, r); }
; __device__ __forceinline__ void phase_ln1(const Params& p, int layer, int row0) {
;     ...
; #pragma unroll
;     for (int c = 0; c < 4; ++c) {
;       int col = c * 512 + lane * 8;
;       float y[8];
; #pragma unroll
;       for (int e = 0; e < 8; ++e) y[e] = (v[c * 8 + e] - mu) * rstd * G[col + e] + B[col + e];
;       *(f32x4*)(XR + (size_t)row * LDF + col) = f32x4{y[0], y[1], y[2], y[3]};
;       *(f32x4*)(XR + (size_t)row * LDF + col + 4) = f32x4{y[4], y[5], y[6], y[7]};
;       float z[8];
; #pragma unroll
;       for (int e = 0; e < 8; ++e) z[e] = y[e] * (1.f + md[8192 + col + e]) + md[6144 + col + e];
;       u32x4 o = {pk2(z[0], z[1]), pk2(z[2], z[3]), pk2(z[4], z[5]), pk2(z[6], z[7])};
;       *(u32x4*)(XM + (size_t)row * LDX + col) = o;
;     }
	v_mov_b32_e32 v60, v166
	v_mov_b32_e32 v61, v167
	v_pk_fma_f32 v[6:7], v[14:15], v[8:9], v[58:59]
	v_pk_fma_f32 v[8:9], v[72:73], v[10:11], v[60:61]
	v_cvt_pk_bf16_f32 v2, v2, v3
	v_cvt_pk_bf16_f32 v3, v4, v5
	v_cvt_pk_bf16_f32 v4, v6, v7
	v_cvt_pk_bf16_f32 v5, v8, v9
	global_store_dwordx4 v[0:1], v[2:5], off
	s_nop 0
	v_lshl_add_u64 v[14:15], v[56:57], 0, s[12:13]
	v_lshl_add_u64 v[76:77], v[56:57], 0, s[14:15]
	v_pk_mul_f32 v[56:57], v[112:113], v[16:17] op_sel_hi:[1,0]
	v_pk_mul_f32 v[72:73], v[114:115], v[16:17] op_sel_hi:[1,0]
	v_pk_mul_f32 v[74:75], v[108:109], v[16:17] op_sel_hi:[1,0]
	v_pk_mul_f32 v[78:79], v[110:111], v[16:17] op_sel_hi:[1,0]
	s_nop 1
	v_mov_b32_e32 v2, v168
	v_mov_b32_e32 v3, v169
	v_mov_b32_e32 v4, v170
	v_mov_b32_e32 v5, v171
	v_mov_b32_e32 v6, v172
	v_mov_b32_e32 v7, v173
	v_mov_b32_e32 v8, v174
	v_mov_b32_e32 v9, v175
	v_pk_fma_f32 v[2:3], v[6:7], v[56:57], v[2:3]
	v_pk_fma_f32 v[4:5], v[8:9], v[72:73], v[4:5]
	s_nop 1
	v_mov_b32_e32 v10, v176
	v_mov_b32_e32 v11, v177
	v_mov_b32_e32 v12, v178
	v_mov_b32_e32 v13, v179
	v_mov_b32_e32 v58, v180
	v_mov_b32_e32 v59, v181
	v_mov_b32_e32 v60, v182
	v_mov_b32_e32 v61, v183
	v_pk_fma_f32 v[6:7], v[10:11], v[74:75], v[58:59]
	v_pk_fma_f32 v[8:9], v[12:13], v[78:79], v[60:61]
	global_store_dwordx4 v[46:47], v[2:5], off offset:2048
	global_store_dwordx4 v[46:47], v[6:9], off offset:2064
	s_nop 0
	s_nop 1
	v_mov_b32_e32 v10, v184
	v_mov_b32_e32 v11, v185
	v_mov_b32_e32 v12, v186
	v_mov_b32_e32 v13, v187
	v_pk_add_f32 v[10:11], v[10:11], 1.0 op_sel_hi:[1,0]
	v_pk_add_f32 v[12:13], v[12:13], 1.0 op_sel_hi:[1,0]
	s_nop 1
	v_mov_b32_e32 v56, v188
	v_mov_b32_e32 v57, v189
	v_mov_b32_e32 v58, v190
	v_mov_b32_e32 v59, v191
	v_pk_add_f32 v[14:15], v[56:57], 1.0 op_sel_hi:[1,0]
	v_pk_add_f32 v[46:47], v[58:59], 1.0 op_sel_hi:[1,0]
	s_nop 1
	v_mov_b32_e32 v72, v192
	v_mov_b32_e32 v73, v193
	v_mov_b32_e32 v74, v194
	v_mov_b32_e32 v75, v195
	v_pk_fma_f32 v[2:3], v[10:11], v[2:3], v[72:73]
	v_pk_fma_f32 v[4:5], v[4:5], v[12:13], v[74:75]
	s_nop 1
	v_mov_b32_e32 v76, v196
	v_mov_b32_e32 v77, v197
	v_mov_b32_e32 v78, v198
	v_mov_b32_e32 v79, v199
	v_pk_fma_f32 v[6:7], v[6:7], v[14:15], v[76:77]
	v_pk_fma_f32 v[8:9], v[8:9], v[46:47], v[78:79]
	v_cvt_pk_bf16_f32 v2, v2, v3
	v_cvt_pk_bf16_f32 v3, v4, v5
	v_cvt_pk_bf16_f32 v4, v6, v7
	v_cvt_pk_bf16_f32 v5, v8, v9
	global_store_dwordx4 v[0:1], v[2:5], off offset:1024
	s_nop 0
	v_lshl_add_u64 v[46:47], v[44:45], 0, v[36:37]
	v_add_co_u32_e32 v72, vcc, s19, v46
	v_pk_mul_f32 v[74:75], v[84:85], v[16:17] op_sel_hi:[1,0]
	v_pk_mul_f32 v[78:79], v[86:87], v[16:17] op_sel_hi:[1,0]
	v_lshl_add_u64 v[14:15], v[42:43], 0, v[36:37]
	v_addc_co_u32_e32 v73, vcc, 0, v47, vcc
	v_lshl_add_u64 v[60:61], v[46:47], 0, s[8:9]
	v_lshl_add_u64 v[76:77], v[46:47], 0, s[10:11]
	v_add_co_u32_e32 v46, vcc, s20, v46
	s_nop 1
	v_mov_b32_e32 v2, v200
	v_mov_b32_e32 v3, v201
	v_mov_b32_e32 v4, v202
	v_mov_b32_e32 v5, v203
	v_mov_b32_e32 v6, v204
	v_mov_b32_e32 v7, v205
	v_mov_b32_e32 v8, v206
	v_mov_b32_e32 v9, v207
	v_pk_fma_f32 v[2:3], v[74:75], v[6:7], v[2:3]
	v_pk_fma_f32 v[4:5], v[78:79], v[8:9], v[4:5]
	s_nop 1
	v_mov_b32_e32 v10, v208
	v_mov_b32_e32 v11, v209
	v_mov_b32_e32 v12, v210
	v_mov_b32_e32 v13, v212
	v_mov_b32_e32 v56, v213
	v_mov_b32_e32 v57, v215
	v_mov_b32_e32 v58, v216
	v_mov_b32_e32 v59, v217
	v_pk_fma_f32 v[6:7], v[80:81], v[10:11], v[56:57]
	v_pk_fma_f32 v[8:9], v[82:83], v[12:13], v[58:59]
	global_store_dwordx4 v[14:15], v[2:5], off
	global_store_dwordx4 v[14:15], v[6:9], off offset:16
	v_addc_co_u32_e32 v47, vcc, 0, v47, vcc
	s_nop 0
	s_nop 0
	s_nop 1
	v_mov_b32_e32 v10, v218
	v_mov_b32_e32 v11, v219
	v_mov_b32_e32 v12, v220
	v_mov_b32_e32 v13, v221
	v_pk_add_f32 v[10:11], v[10:11], 1.0 op_sel_hi:[1,0]
	v_pk_add_f32 v[12:13], v[12:13], 1.0 op_sel_hi:[1,0]
	s_nop 1
	v_mov_b32_e32 v56, v222
	v_mov_b32_e32 v57, v223
	v_mov_b32_e32 v58, v224
	v_mov_b32_e32 v59, v225
	v_pk_add_f32 v[14:15], v[56:57], 1.0 op_sel_hi:[1,0]
	v_pk_add_f32 v[46:47], v[58:59], 1.0 op_sel_hi:[1,0]
	s_nop 1
	v_mov_b32_e32 v72, v226
	v_mov_b32_e32 v73, v227
	v_mov_b32_e32 v74, v228
	v_mov_b32_e32 v75, v229
	v_pk_fma_f32 v[2:3], v[2:3], v[10:11], v[72:73]
	v_pk_fma_f32 v[4:5], v[4:5], v[12:13], v[74:75]
	s_nop 1
	v_mov_b32_e32 v76, v230
	v_mov_b32_e32 v77, v231
	v_mov_b32_e32 v78, v232
	v_mov_b32_e32 v79, v233
	v_pk_fma_f32 v[6:7], v[6:7], v[14:15], v[76:77]
	v_pk_fma_f32 v[8:9], v[8:9], v[46:47], v[78:79]
	v_cvt_pk_bf16_f32 v2, v2, v3
	v_cvt_pk_bf16_f32 v3, v4, v5
	v_cvt_pk_bf16_f32 v4, v6, v7
	v_cvt_pk_bf16_f32 v5, v8, v9
	global_store_dwordx4 v[0:1], v[2:5], off offset:2048
	s_nop 0
	v_lshl_add_u64 v[14:15], v[42:43], 0, v[38:39]
	v_lshl_add_u64 v[42:43], v[44:45], 0, v[38:39]
	v_add_co_u32_e32 v46, vcc, s19, v42
	v_lshl_add_u64 v[44:45], v[42:43], 0, s[8:9]
	s_nop 0
	v_addc_co_u32_e32 v47, vcc, 0, v43, vcc
	v_add_co_u32_e32 v72, vcc, s20, v42
	v_lshl_add_u64 v[60:61], v[42:43], 0, s[10:11]
	s_nop 0
	v_addc_co_u32_e32 v73, vcc, 0, v43, vcc
	v_pk_mul_f32 v[42:43], v[52:53], v[16:17] op_sel_hi:[1,0]
	v_pk_mul_f32 v[52:53], v[54:55], v[16:17] op_sel_hi:[1,0]
	v_cmp_lt_i32_e32 vcc, s21, v62
	s_or_b64 s[0:1], vcc, s[0:1]
	s_nop 1
	v_mov_b32_e32 v2, v234
	v_mov_b32_e32 v3, v235
	v_mov_b32_e32 v4, v236
	v_mov_b32_e32 v5, v237
	v_mov_b32_e32 v6, v238
	v_mov_b32_e32 v7, v240
	v_mov_b32_e32 v8, v241
	v_mov_b32_e32 v9, v242
	v_pk_fma_f32 v[2:3], v[42:43], v[6:7], v[2:3]
	v_pk_fma_f32 v[4:5], v[52:53], v[8:9], v[4:5]
	s_nop 1
	v_mov_b32_e32 v10, v243
	v_mov_b32_e32 v11, v244
	v_mov_b32_e32 v12, v245
	v_mov_b32_e32 v13, v246
	v_mov_b32_e32 v56, v247
	v_mov_b32_e32 v57, v248
	v_mov_b32_e32 v58, v249
	v_mov_b32_e32 v59, v250
	v_pk_fma_f32 v[6:7], v[48:49], v[10:11], v[56:57]
	v_pk_fma_f32 v[8:9], v[50:51], v[12:13], v[58:59]
	global_store_dwordx4 v[14:15], v[2:5], off
	global_store_dwordx4 v[14:15], v[6:9], off offset:16
	global_load_dwordx4 v[10:13], v[46:47], off
	s_nop 0
	global_load_dwordx4 v[42:45], v[44:45], off offset:16
	s_nop 0
	global_load_dwordx4 v[46:49], v[72:73], off
	global_load_dwordx4 v[50:53], v[60:61], off offset:16
	s_waitcnt vmcnt(3)
	v_pk_add_f32 v[10:11], v[10:11], 1.0 op_sel_hi:[1,0]
	v_pk_add_f32 v[12:13], v[12:13], 1.0 op_sel_hi:[1,0]
	s_waitcnt vmcnt(2)
	v_pk_add_f32 v[14:15], v[42:43], 1.0 op_sel_hi:[1,0]
	v_pk_add_f32 v[42:43], v[44:45], 1.0 op_sel_hi:[1,0]
	s_waitcnt vmcnt(1)
	v_pk_fma_f32 v[2:3], v[2:3], v[10:11], v[46:47]
	v_pk_fma_f32 v[4:5], v[4:5], v[12:13], v[48:49]
	s_waitcnt vmcnt(0)
	v_pk_fma_f32 v[6:7], v[6:7], v[14:15], v[50:51]
	v_pk_fma_f32 v[8:9], v[8:9], v[42:43], v[52:53]
	v_cvt_pk_bf16_f32 v2, v2, v3
	v_cvt_pk_bf16_f32 v3, v4, v5
	v_cvt_pk_bf16_f32 v4, v6, v7
	v_cvt_pk_bf16_f32 v5, v8, v9
	global_store_dwordx4 v[0:1], v[2:5], off offset:3072
	s_andn2_b64 exec, exec, s[0:1]
	s_cbranch_execnz .Lln1_B0

; DI const float* modp(const Params& p, int layer, int v) { return (const float*)(p.ws + OFF_MOD) + (size_t)(layer * 2 + v) * 12288; }
; __device__ __forceinline__ void phase_ln1(const Params& p, int layer, int row0) {
;     ...
;   for (int row = row0 + blockIdx.x * 4 + wid; row < TT; row += gridDim.x * 4) {
;     const float* md = modp(p, layer, row < NCTX ? 1 : 0);
;     float v[32];
;     float s = 0.f;
; #pragma unroll
;     for (int c = 0; c < 4; ++c) {
;       int col = c * 512 + lane * 8;
;       f32x4 a = *(const f32x4*)(PRE + (size_t)row * LDF + col), b = *(const f32x4*)(PRE + (size_t)row * LDF + col + 4);
; #pragma unroll
;       for (int e = 0; e < 4; ++e) { v[c * 8 + e] = a[e]; v[c * 8 + 4 + e] = b[e]; s += a[e] + b[e]; }
;     }
;     const float mu = wave_sum(s) * (1.f / 2048.f);
;     float q = 0.f;
; #pragma unroll
;     for (int e = 0; e < 32; ++e) { float d = v[e] - mu; q += d * d; }
;     const float rstd = rsqrtf(wave_sum(q) * (1.f / 2048.f) + LN_EPS);
.LBB0_2441:
	v_mad_i64_i32 v[48:49], s[22:23], v66, s16, v[36:37]
	v_lshl_add_u64 v[60:61], v[48:49], 0, v[38:39]
	global_load_dwordx4 v[0:3], v[18:19], off offset:16
	global_load_dwordx4 v[4:7], v[18:19], off
	global_load_dwordx4 v[8:11], v[20:21], off offset:16
	global_load_dwordx4 v[12:15], v[20:21], off
	v_lshl_add_u64 v[62:63], v[48:49], 0, v[40:41]
	v_lshl_add_u64 v[64:65], v[48:49], 0, v[42:43]
	global_load_dwordx4 v[52:55], v[60:61], off offset:16
	global_load_dwordx4 v[56:59], v[60:61], off
	global_load_dwordx4 v[76:79], v[60:61], off offset:2064
	global_load_dwordx4 v[80:83], v[60:61], off offset:2048
	global_load_dwordx4 v[84:87], v[62:63], off offset:16
	global_load_dwordx4 v[88:91], v[62:63], off
	global_load_dwordx4 v[92:95], v[64:65], off offset:16
	global_load_dwordx4 v[96:99], v[64:65], off
	v_cmp_gt_i32_e32 vcc, s14, v66
	v_mad_i64_i32 v[46:47], s[22:23], v66, s16, v[44:45]
	s_nop 0
	v_cndmask_b32_e32 v16, v73, v74, vcc
	v_lshl_add_u64 v[48:49], s[4:5], 0, v[16:17]
	v_lshl_add_u64 v[60:61], v[48:49], 0, v[38:39]
	v_add_co_u32_e32 v100, vcc, s19, v60
	v_lshl_add_u64 v[50:51], v[46:47], 0, v[38:39]
	s_nop 0
	v_addc_co_u32_e32 v101, vcc, 0, v61, vcc
	v_add_co_u32_e32 v102, vcc, s20, v60
	v_lshl_add_u64 v[62:63], v[60:61], 0, s[6:7]
	s_nop 0
	v_addc_co_u32_e32 v103, vcc, 0, v61, vcc
	v_lshl_add_u64 v[64:65], v[60:61], 0, s[8:9]
	s_waitcnt vmcnt(6)
	v_mov_b32_e32 v136, v0
	v_mov_b32_e32 v137, v1
	v_mov_b32_e32 v138, v2
	v_mov_b32_e32 v139, v3
	v_mov_b32_e32 v140, v4
	v_mov_b32_e32 v141, v5
	v_mov_b32_e32 v142, v6
	v_mov_b32_e32 v143, v7
	v_mov_b32_e32 v144, v8
	v_mov_b32_e32 v145, v9
	v_mov_b32_e32 v146, v10
	v_mov_b32_e32 v147, v11
	v_mov_b32_e32 v148, v12
	v_mov_b32_e32 v149, v13
	v_mov_b32_e32 v150, v14
	v_mov_b32_e32 v151, v15
	v_add_f32_e32 v16, v56, v52
	v_add_f32_e32 v108, v57, v53
	v_add_f32_e32 v16, 0, v16
	v_add_f32_e32 v109, v58, v54
	v_add_f32_e32 v16, v108, v16
	v_add_f32_e32 v110, v59, v55
	v_add_f32_e32 v16, v109, v16
	s_waitcnt vmcnt(4)
	v_add_f32_e32 v111, v80, v76
	v_add_f32_e32 v16, v110, v16
	v_add_f32_e32 v112, v81, v77
	v_add_f32_e32 v16, v111, v16
	v_add_f32_e32 v113, v82, v78
	v_add_f32_e32 v16, v112, v16
	v_add_f32_e32 v114, v83, v79
	v_add_f32_e32 v16, v113, v16
	s_waitcnt vmcnt(2)
	v_add_f32_e32 v115, v88, v84
	v_add_f32_e32 v16, v114, v16
	v_add_f32_e32 v116, v89, v85
	v_add_f32_e32 v16, v115, v16
	v_add_f32_e32 v117, v90, v86
	v_add_f32_e32 v16, v116, v16
	v_add_f32_e32 v118, v91, v87
	v_add_f32_e32 v16, v117, v16
	s_waitcnt vmcnt(0)
	v_pk_add_f32 v[104:105], v[96:97], v[92:93]
	v_add_f32_e32 v16, v118, v16
	v_add_f32_e32 v16, v104, v16
	v_pk_add_f32 v[106:107], v[98:99], v[94:95]
	v_add_f32_e32 v16, v105, v16
	v_add_f32_e32 v16, v106, v16
	v_add_f32_e32 v16, v107, v16
	ds_bpermute_b32 v104, v67, v16
	s_waitcnt lgkmcnt(0)
	v_add_f32_e32 v16, v16, v104
	ds_bpermute_b32 v104, v68, v16
	s_waitcnt lgkmcnt(0)
	v_add_f32_e32 v16, v16, v104
	ds_bpermute_b32 v104, v69, v16
	s_waitcnt lgkmcnt(0)
	v_add_f32_e32 v16, v16, v104
	ds_bpermute_b32 v104, v70, v16
	s_waitcnt lgkmcnt(0)
	v_add_f32_e32 v16, v16, v104
	ds_bpermute_b32 v104, v71, v16
	s_waitcnt lgkmcnt(0)
	v_add_f32_e32 v16, v16, v104
	ds_bpermute_b32 v104, v72, v16
	s_waitcnt lgkmcnt(0)
	v_add_f32_e32 v16, v16, v104
	v_mul_f32_e32 v16, 0x3a000000, v16
	v_pk_add_f32 v[108:109], v[56:57], v[16:17] op_sel_hi:[1,0] neg_lo:[0,1] neg_hi:[0,1]
	v_pk_add_f32 v[110:111], v[58:59], v[16:17] op_sel_hi:[1,0] neg_lo:[0,1] neg_hi:[0,1]
	v_pk_add_f32 v[116:117], v[80:81], v[16:17] op_sel_hi:[1,0] neg_lo:[0,1] neg_hi:[0,1]
	v_pk_mul_f32 v[80:81], v[108:109], v[108:109]
	v_pk_add_f32 v[104:105], v[52:53], v[16:17] op_sel_hi:[1,0] neg_lo:[0,1] neg_hi:[0,1]
	v_pk_add_f32 v[106:107], v[54:55], v[16:17] op_sel_hi:[1,0] neg_lo:[0,1] neg_hi:[0,1]
	v_pk_add_f32 v[112:113], v[76:77], v[16:17] op_sel_hi:[1,0] neg_lo:[0,1] neg_hi:[0,1]
	v_pk_add_f32 v[114:115], v[78:79], v[16:17] op_sel_hi:[1,0] neg_lo:[0,1] neg_hi:[0,1]
	v_pk_add_f32 v[118:119], v[82:83], v[16:17] op_sel_hi:[1,0] neg_lo:[0,1] neg_hi:[0,1]
	v_pk_add_f32 v[120:121], v[84:85], v[16:17] op_sel_hi:[1,0] neg_lo:[0,1] neg_hi:[0,1]
	v_pk_add_f32 v[122:123], v[86:87], v[16:17] op_sel_hi:[1,0] neg_lo:[0,1] neg_hi:[0,1]
	v_pk_add_f32 v[88:89], v[88:89], v[16:17] op_sel_hi:[1,0] neg_lo:[0,1] neg_hi:[0,1]
	v_pk_add_f32 v[90:91], v[90:91], v[16:17] op_sel_hi:[1,0] neg_lo:[0,1] neg_hi:[0,1]
	v_pk_add_f32 v[52:53], v[92:93], v[16:17] op_sel_hi:[1,0] neg_lo:[0,1] neg_hi:[0,1]
	v_pk_add_f32 v[54:55], v[94:95], v[16:17] op_sel_hi:[1,0] neg_lo:[0,1] neg_hi:[0,1]
	v_pk_add_f32 v[56:57], v[96:97], v[16:17] op_sel_hi:[1,0] neg_lo:[0,1] neg_hi:[0,1]
	v_pk_add_f32 v[58:59], v[98:99], v[16:17] op_sel_hi:[1,0] neg_lo:[0,1] neg_hi:[0,1]
	v_pk_mul_f32 v[82:83], v[110:111], v[110:111]
	v_add_f32_e32 v16, v80, v81
	v_add_f32_e32 v16, v82, v16
	v_pk_mul_f32 v[76:77], v[104:105], v[104:105]
	v_add_f32_e32 v16, v83, v16
	v_add_f32_e32 v16, v76, v16
	v_pk_mul_f32 v[78:79], v[106:107], v[106:107]
	v_add_f32_e32 v16, v77, v16
	v_add_f32_e32 v16, v78, v16
	v_pk_mul_f32 v[92:93], v[116:117], v[116:117]
	v_add_f32_e32 v16, v79, v16
	v_add_f32_e32 v16, v92, v16
	v_pk_mul_f32 v[94:95], v[118:119], v[118:119]
	v_add_f32_e32 v16, v93, v16
	v_add_f32_e32 v16, v94, v16
	v_pk_mul_f32 v[84:85], v[112:113], v[112:113]
	v_add_f32_e32 v16, v95, v16
	v_add_f32_e32 v16, v84, v16
	v_pk_mul_f32 v[86:87], v[114:115], v[114:115]
	v_add_f32_e32 v16, v85, v16
	v_add_f32_e32 v16, v86, v16
	v_pk_mul_f32 v[124:125], v[88:89], v[88:89]
	v_add_f32_e32 v16, v87, v16
	v_add_f32_e32 v16, v124, v16
	v_pk_mul_f32 v[126:127], v[90:91], v[90:91]
	v_add_f32_e32 v16, v125, v16
	v_add_f32_e32 v16, v126, v16
	v_pk_mul_f32 v[96:97], v[120:121], v[120:121]
	v_add_f32_e32 v16, v127, v16
	v_add_f32_e32 v16, v96, v16
	v_pk_mul_f32 v[98:99], v[122:123], v[122:123]
	v_add_f32_e32 v16, v97, v16
	v_add_f32_e32 v16, v98, v16
	v_pk_mul_f32 v[132:133], v[56:57], v[56:57]
	v_add_f32_e32 v16, v99, v16
	v_add_f32_e32 v16, v132, v16
	v_pk_mul_f32 v[134:135], v[58:59], v[58:59]
	v_add_f32_e32 v16, v133, v16
	v_add_f32_e32 v16, v134, v16
	v_pk_mul_f32 v[128:129], v[52:53], v[52:53]
	v_add_f32_e32 v16, v135, v16
	v_add_f32_e32 v16, v128, v16
	v_pk_mul_f32 v[130:131], v[54:55], v[54:55]
	v_add_f32_e32 v16, v129, v16
	v_add_f32_e32 v16, v130, v16
	v_add_f32_e32 v16, v131, v16
	ds_bpermute_b32 v76, v67, v16
	s_waitcnt lgkmcnt(0)
; DI unsigned pk2(float a, float b) { f32x2 v = {a, b}; bf2_t r = __builtin_convertvector(v, bf2_t); return __builtin_bit_cast(unsigned, r); }
; __device__ __forceinline__ void phase_ln1(const Params& p, int layer, int row0) {
;     ...
;     const float rstd = rsqrtf(wave_sum(q) * (1.f / 2048.f) + LN_EPS);
; #pragma unroll
;     for (int c = 0; c < 4; ++c) {
;       int col = c * 512 + lane * 8;
;       float y[8];
; #pragma unroll
;       for (int e = 0; e < 8; ++e) y[e] = (v[c * 8 + e] - mu) * rstd * G[col + e] + B[col + e];
;       *(f32x4*)(XR + (size_t)row * LDF + col) = f32x4{y[0], y[1], y[2], y[3]};
;       *(f32x4*)(XR + (size_t)row * LDF + col + 4) = f32x4{y[4], y[5], y[6], y[7]};
;       float z[8];
; #pragma unroll
;       for (int e = 0; e < 8; ++e) z[e] = y[e] * (1.f + md[8192 + col + e]) + md[6144 + col + e];
;       u32x4 o = {pk2(z[0], z[1]), pk2(z[2], z[3]), pk2(z[4], z[5]), pk2(z[6], z[7])};
;       *(u32x4*)(XM + (size_t)row * LDX + col) = o;
	v_add_f32_e32 v16, v16, v76
	ds_bpermute_b32 v76, v68, v16
	s_waitcnt lgkmcnt(0)
	v_add_f32_e32 v16, v16, v76
	ds_bpermute_b32 v76, v69, v16
	s_waitcnt lgkmcnt(0)
	v_add_f32_e32 v16, v16, v76
	ds_bpermute_b32 v76, v70, v16
	s_waitcnt lgkmcnt(0)
	v_add_f32_e32 v16, v16, v76
	ds_bpermute_b32 v76, v71, v16
	s_waitcnt lgkmcnt(0)
	v_add_f32_e32 v16, v16, v76
	ds_bpermute_b32 v76, v72, v16
	s_waitcnt lgkmcnt(0)
	v_add_f32_e32 v16, v16, v76
	v_fmamk_f32 v16, v16, 0x3a000000, v75
	v_mul_f32_e32 v76, 0x4b800000, v16
	v_cmp_gt_f32_e32 vcc, s18, v16
	s_nop 1
	v_cndmask_b32_e32 v16, v16, v76, vcc
	v_rsq_f32_e32 v16, v16
	s_nop 0
	v_mul_f32_e32 v76, 0x45800000, v16
	v_cndmask_b32_e32 v16, v16, v76, vcc
	v_pk_mul_f32 v[76:77], v[108:109], v[16:17] op_sel_hi:[1,0]
	v_pk_mul_f32 v[78:79], v[110:111], v[16:17] op_sel_hi:[1,0]
	v_pk_mul_f32 v[80:81], v[104:105], v[16:17] op_sel_hi:[1,0]
	v_pk_mul_f32 v[82:83], v[106:107], v[16:17] op_sel_hi:[1,0]
	v_pk_fma_f32 v[4:5], v[4:5], v[76:77], v[12:13]
	v_pk_fma_f32 v[6:7], v[6:7], v[78:79], v[14:15]
	v_pk_fma_f32 v[8:9], v[0:1], v[80:81], v[8:9]
	v_pk_fma_f32 v[10:11], v[2:3], v[82:83], v[10:11]
	global_store_dwordx4 v[50:51], v[4:7], off
	global_store_dwordx4 v[50:51], v[8:11], off offset:16
	global_load_dwordx4 v[12:15], v[100:101], off
	global_load_dwordx4 v[76:79], v[62:63], off offset:16
	global_load_dwordx4 v[80:83], v[102:103], off
	global_load_dwordx4 v[84:87], v[64:65], off offset:16
	v_mad_i64_i32 v[0:1], s[22:23], v66, s17, v[34:35]
	v_add_u32_e32 v66, s15, v66
	s_waitcnt vmcnt(3)
	v_mov_b32_e32 v152, v12
	v_mov_b32_e32 v153, v13
	v_mov_b32_e32 v154, v14
	v_mov_b32_e32 v155, v15
	v_pk_add_f32 v[2:3], v[12:13], 1.0 op_sel_hi:[1,0]
	v_pk_add_f32 v[12:13], v[14:15], 1.0 op_sel_hi:[1,0]
	s_waitcnt vmcnt(2)
	v_mov_b32_e32 v156, v76
	v_mov_b32_e32 v157, v77
	v_mov_b32_e32 v158, v78
	v_mov_b32_e32 v159, v79
	v_pk_add_f32 v[14:15], v[76:77], 1.0 op_sel_hi:[1,0]
	v_pk_add_f32 v[62:63], v[78:79], 1.0 op_sel_hi:[1,0]
	s_waitcnt vmcnt(1)
	v_mov_b32_e32 v160, v80
	v_mov_b32_e32 v161, v81
	v_mov_b32_e32 v162, v82
	v_mov_b32_e32 v163, v83
	v_pk_fma_f32 v[2:3], v[2:3], v[4:5], v[80:81]
	v_pk_fma_f32 v[4:5], v[12:13], v[6:7], v[82:83]
	s_waitcnt vmcnt(0)
	v_mov_b32_e32 v164, v84
	v_mov_b32_e32 v165, v85
	v_mov_b32_e32 v166, v86
	v_mov_b32_e32 v167, v87
	v_pk_fma_f32 v[6:7], v[14:15], v[8:9], v[84:85]
	v_pk_fma_f32 v[8:9], v[62:63], v[10:11], v[86:87]
	v_cvt_pk_bf16_f32 v2, v2, v3
	v_cvt_pk_bf16_f32 v3, v4, v5
	v_cvt_pk_bf16_f32 v4, v6, v7
	v_cvt_pk_bf16_f32 v5, v8, v9
	global_store_dwordx4 v[0:1], v[2:5], off
	global_load_dwordx4 v[2:5], v[24:25], off
	s_nop 0
	global_load_dwordx4 v[6:9], v[22:23], off
	global_load_dwordx4 v[10:13], v[22:23], off offset:16
	global_load_dwordx4 v[62:65], v[24:25], off offset:16
	v_lshl_add_u64 v[14:15], v[60:61], 0, s[10:11]
	v_lshl_add_u64 v[84:85], v[60:61], 0, s[12:13]
	v_pk_mul_f32 v[60:61], v[116:117], v[16:17] op_sel_hi:[1,0]
	v_pk_mul_f32 v[76:77], v[118:119], v[16:17] op_sel_hi:[1,0]
	v_pk_mul_f32 v[78:79], v[112:113], v[16:17] op_sel_hi:[1,0]
	v_pk_mul_f32 v[80:81], v[114:115], v[16:17] op_sel_hi:[1,0]
	s_waitcnt vmcnt(2)
	v_mov_b32_e32 v168, v2
	v_mov_b32_e32 v169, v3
	v_mov_b32_e32 v170, v4
	v_mov_b32_e32 v171, v5
	v_mov_b32_e32 v172, v6
	v_mov_b32_e32 v173, v7
	v_mov_b32_e32 v174, v8
	v_mov_b32_e32 v175, v9
	v_pk_fma_f32 v[2:3], v[6:7], v[60:61], v[2:3]
	v_pk_fma_f32 v[4:5], v[8:9], v[76:77], v[4:5]
	s_waitcnt vmcnt(0)
	v_mov_b32_e32 v176, v10
	v_mov_b32_e32 v177, v11
	v_mov_b32_e32 v178, v12
	v_mov_b32_e32 v179, v13
	v_mov_b32_e32 v180, v62
	v_mov_b32_e32 v181, v63
	v_mov_b32_e32 v182, v64
	v_mov_b32_e32 v183, v65
	v_pk_fma_f32 v[6:7], v[10:11], v[78:79], v[62:63]
	v_pk_fma_f32 v[8:9], v[12:13], v[80:81], v[64:65]
	global_store_dwordx4 v[50:51], v[2:5], off offset:2048
	global_store_dwordx4 v[50:51], v[6:9], off offset:2064
	global_load_dwordx4 v[10:13], v[100:101], off offset:2048
	global_load_dwordx4 v[60:63], v[14:15], off offset:16
	global_load_dwordx4 v[76:79], v[102:103], off offset:2048
	global_load_dwordx4 v[80:83], v[84:85], off offset:16
	s_waitcnt vmcnt(3)
	v_mov_b32_e32 v184, v10
	v_mov_b32_e32 v185, v11
	v_mov_b32_e32 v186, v12
	v_mov_b32_e32 v187, v13
	v_pk_add_f32 v[10:11], v[10:11], 1.0 op_sel_hi:[1,0]
	v_pk_add_f32 v[12:13], v[12:13], 1.0 op_sel_hi:[1,0]
	s_waitcnt vmcnt(2)
	v_mov_b32_e32 v188, v60
	v_mov_b32_e32 v189, v61
	v_mov_b32_e32 v190, v62
	v_mov_b32_e32 v191, v63
	v_pk_add_f32 v[14:15], v[60:61], 1.0 op_sel_hi:[1,0]
	v_pk_add_f32 v[50:51], v[62:63], 1.0 op_sel_hi:[1,0]
	s_waitcnt vmcnt(1)
	v_mov_b32_e32 v192, v76
	v_mov_b32_e32 v193, v77
	v_mov_b32_e32 v194, v78
	v_mov_b32_e32 v195, v79
	v_pk_fma_f32 v[2:3], v[10:11], v[2:3], v[76:77]
	v_pk_fma_f32 v[4:5], v[4:5], v[12:13], v[78:79]
	s_waitcnt vmcnt(0)
	v_mov_b32_e32 v196, v80
	v_mov_b32_e32 v197, v81
	v_mov_b32_e32 v198, v82
	v_mov_b32_e32 v199, v83
	v_pk_fma_f32 v[6:7], v[6:7], v[14:15], v[80:81]
	v_pk_fma_f32 v[8:9], v[8:9], v[50:51], v[82:83]
	v_cvt_pk_bf16_f32 v2, v2, v3
	v_cvt_pk_bf16_f32 v3, v4, v5
	v_cvt_pk_bf16_f32 v4, v6, v7
	v_cvt_pk_bf16_f32 v5, v8, v9
	global_store_dwordx4 v[0:1], v[2:5], off offset:1024
	global_load_dwordx4 v[2:5], v[28:29], off
	s_nop 0
	global_load_dwordx4 v[6:9], v[26:27], off
	global_load_dwordx4 v[10:13], v[26:27], off offset:16
	global_load_dwordx4 v[60:63], v[28:29], off offset:16
	v_lshl_add_u64 v[50:51], v[48:49], 0, v[40:41]
	v_add_co_u32_e32 v86, vcc, s19, v50
	v_pk_mul_f32 v[76:77], v[88:89], v[16:17] op_sel_hi:[1,0]
	v_pk_mul_f32 v[78:79], v[90:91], v[16:17] op_sel_hi:[1,0]
	v_lshl_add_u64 v[14:15], v[46:47], 0, v[40:41]
	v_addc_co_u32_e32 v87, vcc, 0, v51, vcc
	v_pk_mul_f32 v[80:81], v[120:121], v[16:17] op_sel_hi:[1,0]
	v_pk_mul_f32 v[82:83], v[122:123], v[16:17] op_sel_hi:[1,0]
	v_lshl_add_u64 v[64:65], v[50:51], 0, s[6:7]
	v_lshl_add_u64 v[84:85], v[50:51], 0, s[8:9]
	v_add_co_u32_e32 v50, vcc, s20, v50
	s_waitcnt vmcnt(2)
; DI unsigned pk2(float a, float b) { f32x2 v = {a, b}; bf2_t r = __builtin_convertvector(v, bf2_t); return __builtin_bit_cast(unsigned, r); }
; __device__ __forceinline__ void phase_ln1(const Params& p, int layer, int row0) {
;     ...
; #pragma unroll
;     for (int c = 0; c < 4; ++c) {
;       int col = c * 512 + lane * 8;
;       float y[8];
; #pragma unroll
;       for (int e = 0; e < 8; ++e) y[e] = (v[c * 8 + e] - mu) * rstd * G[col + e] + B[col + e];
;       *(f32x4*)(XR + (size_t)row * LDF + col) = f32x4{y[0], y[1], y[2], y[3]};
;       *(f32x4*)(XR + (size_t)row * LDF + col + 4) = f32x4{y[4], y[5], y[6], y[7]};
;       float z[8];
; #pragma unroll
;       for (int e = 0; e < 8; ++e) z[e] = y[e] * (1.f + md[8192 + col + e]) + md[6144 + col + e];
;       u32x4 o = {pk2(z[0], z[1]), pk2(z[2], z[3]), pk2(z[4], z[5]), pk2(z[6], z[7])};
;       *(u32x4*)(XM + (size_t)row * LDX + col) = o;
;     }
	v_mov_b32_e32 v200, v2
	v_mov_b32_e32 v201, v3
	v_mov_b32_e32 v202, v4
	v_mov_b32_e32 v203, v5
	v_mov_b32_e32 v204, v6
	v_mov_b32_e32 v205, v7
	v_mov_b32_e32 v206, v8
	v_mov_b32_e32 v207, v9
	v_pk_fma_f32 v[2:3], v[76:77], v[6:7], v[2:3]
	v_pk_fma_f32 v[4:5], v[78:79], v[8:9], v[4:5]
	s_waitcnt vmcnt(0)
	v_mov_b32_e32 v208, v10
	v_mov_b32_e32 v209, v11
	v_mov_b32_e32 v210, v12
	v_mov_b32_e32 v212, v13
	v_mov_b32_e32 v213, v60
	v_mov_b32_e32 v215, v61
	v_mov_b32_e32 v216, v62
	v_mov_b32_e32 v217, v63
	v_pk_fma_f32 v[6:7], v[80:81], v[10:11], v[60:61]
	v_pk_fma_f32 v[8:9], v[82:83], v[12:13], v[62:63]
	global_store_dwordx4 v[14:15], v[2:5], off
	global_store_dwordx4 v[14:15], v[6:9], off offset:16
	v_addc_co_u32_e32 v51, vcc, 0, v51, vcc
	global_load_dwordx4 v[10:13], v[86:87], off
	global_load_dwordx4 v[60:63], v[64:65], off offset:16
	global_load_dwordx4 v[76:79], v[50:51], off
	global_load_dwordx4 v[80:83], v[84:85], off offset:16
	s_waitcnt vmcnt(3)
	v_mov_b32_e32 v218, v10
	v_mov_b32_e32 v219, v11
	v_mov_b32_e32 v220, v12
	v_mov_b32_e32 v221, v13
	v_pk_add_f32 v[10:11], v[10:11], 1.0 op_sel_hi:[1,0]
	v_pk_add_f32 v[12:13], v[12:13], 1.0 op_sel_hi:[1,0]
	s_waitcnt vmcnt(2)
	v_mov_b32_e32 v222, v60
	v_mov_b32_e32 v223, v61
	v_mov_b32_e32 v224, v62
	v_mov_b32_e32 v225, v63
	v_pk_add_f32 v[14:15], v[60:61], 1.0 op_sel_hi:[1,0]
	v_pk_add_f32 v[50:51], v[62:63], 1.0 op_sel_hi:[1,0]
	s_waitcnt vmcnt(1)
	v_mov_b32_e32 v226, v76
	v_mov_b32_e32 v227, v77
	v_mov_b32_e32 v228, v78
	v_mov_b32_e32 v229, v79
	v_pk_fma_f32 v[2:3], v[2:3], v[10:11], v[76:77]
	v_pk_fma_f32 v[4:5], v[4:5], v[12:13], v[78:79]
	s_waitcnt vmcnt(0)
	v_mov_b32_e32 v230, v80
	v_mov_b32_e32 v231, v81
	v_mov_b32_e32 v232, v82
	v_mov_b32_e32 v233, v83
	v_pk_fma_f32 v[6:7], v[6:7], v[14:15], v[80:81]
	v_pk_fma_f32 v[8:9], v[8:9], v[50:51], v[82:83]
	v_cvt_pk_bf16_f32 v2, v2, v3
	v_cvt_pk_bf16_f32 v3, v4, v5
	v_cvt_pk_bf16_f32 v4, v6, v7
	v_cvt_pk_bf16_f32 v5, v8, v9
	global_store_dwordx4 v[0:1], v[2:5], off offset:2048
	global_load_dwordx4 v[2:5], v[32:33], off
	s_nop 0
	global_load_dwordx4 v[6:9], v[30:31], off
	global_load_dwordx4 v[10:13], v[30:31], off offset:16
	global_load_dwordx4 v[60:63], v[32:33], off offset:16
	v_lshl_add_u64 v[14:15], v[46:47], 0, v[42:43]
	v_lshl_add_u64 v[46:47], v[48:49], 0, v[42:43]
	v_add_co_u32_e32 v78, vcc, s19, v46
	v_lshl_add_u64 v[64:65], v[46:47], 0, s[6:7]
	s_nop 0
	v_addc_co_u32_e32 v79, vcc, 0, v47, vcc
	v_add_co_u32_e32 v80, vcc, s20, v46
	v_lshl_add_u64 v[76:77], v[46:47], 0, s[8:9]
	s_nop 0
	v_addc_co_u32_e32 v81, vcc, 0, v47, vcc
	v_pk_mul_f32 v[46:47], v[56:57], v[16:17] op_sel_hi:[1,0]
	v_pk_mul_f32 v[48:49], v[58:59], v[16:17] op_sel_hi:[1,0]
	v_pk_mul_f32 v[50:51], v[52:53], v[16:17] op_sel_hi:[1,0]
	v_pk_mul_f32 v[52:53], v[54:55], v[16:17] op_sel_hi:[1,0]
	v_cmp_lt_i32_e32 vcc, s21, v66
	s_or_b64 s[0:1], vcc, s[0:1]
	s_waitcnt vmcnt(2)
	v_mov_b32_e32 v234, v2
	v_mov_b32_e32 v235, v3
	v_mov_b32_e32 v236, v4
	v_mov_b32_e32 v237, v5
	v_mov_b32_e32 v238, v6
	v_mov_b32_e32 v240, v7
	v_mov_b32_e32 v241, v8
	v_mov_b32_e32 v242, v9
	v_pk_fma_f32 v[2:3], v[46:47], v[6:7], v[2:3]
	v_pk_fma_f32 v[4:5], v[48:49], v[8:9], v[4:5]
	s_waitcnt vmcnt(0)
	v_mov_b32_e32 v243, v10
	v_mov_b32_e32 v244, v11
	v_mov_b32_e32 v245, v12
	v_mov_b32_e32 v246, v13
	v_mov_b32_e32 v247, v60
	v_mov_b32_e32 v248, v61
	v_mov_b32_e32 v249, v62
	v_mov_b32_e32 v250, v63
	v_pk_fma_f32 v[6:7], v[50:51], v[10:11], v[60:61]
	v_pk_fma_f32 v[8:9], v[52:53], v[12:13], v[62:63]
	global_store_dwordx4 v[14:15], v[2:5], off
	global_store_dwordx4 v[14:15], v[6:9], off offset:16
	global_load_dwordx4 v[10:13], v[78:79], off
	global_load_dwordx4 v[46:49], v[64:65], off offset:16
	global_load_dwordx4 v[50:53], v[80:81], off
	global_load_dwordx4 v[54:57], v[76:77], off offset:16
	s_waitcnt vmcnt(3)
	v_pk_add_f32 v[10:11], v[10:11], 1.0 op_sel_hi:[1,0]
	v_pk_add_f32 v[12:13], v[12:13], 1.0 op_sel_hi:[1,0]
	s_waitcnt vmcnt(2)
	v_pk_add_f32 v[14:15], v[46:47], 1.0 op_sel_hi:[1,0]
	v_pk_add_f32 v[46:47], v[48:49], 1.0 op_sel_hi:[1,0]
	s_waitcnt vmcnt(1)
	v_pk_fma_f32 v[2:3], v[2:3], v[10:11], v[50:51]
	v_pk_fma_f32 v[4:5], v[4:5], v[12:13], v[52:53]
	s_waitcnt vmcnt(0)
	v_pk_fma_f32 v[6:7], v[6:7], v[14:15], v[54:55]
	v_pk_fma_f32 v[8:9], v[8:9], v[46:47], v[56:57]
	v_cvt_pk_bf16_f32 v2, v2, v3
	v_cvt_pk_bf16_f32 v3, v4, v5
	v_cvt_pk_bf16_f32 v4, v6, v7
	v_cvt_pk_bf16_f32 v5, v8, v9
	global_store_dwordx4 v[0:1], v[2:5], off offset:3072
	s_andn2_b64 exec, exec, s[0:1]
	s_cbranch_execnz .Lln1_B1
	s_branch .LBB0_2442
; DI const float* modp(const Params& p, int layer, int v) { return (const float*)(p.ws + OFF_MOD) + (size_t)(layer * 2 + v) * 12288; }
; __device__ __forceinline__ void phase_ln1(const Params& p, int layer, int row0) {
;     ...
;   for (int row = row0 + blockIdx.x * 4 + wid; row < TT; row += gridDim.x * 4) {
;     const float* md = modp(p, layer, row < NCTX ? 1 : 0);
;     float v[32];
;     float s = 0.f;
; #pragma unroll
;     for (int c = 0; c < 4; ++c) {
;       int col = c * 512 + lane * 8;
;       f32x4 a = *(const f32x4*)(PRE + (size_t)row * LDF + col), b = *(const f32x4*)(PRE + (size_t)row * LDF + col + 4);
; #pragma unroll
;       for (int e = 0; e < 4; ++e) { v[c * 8 + e] = a[e]; v[c * 8 + 4 + e] = b[e]; s += a[e] + b[e]; }
;     }
;     const float mu = wave_sum(s) * (1.f / 2048.f);
;     float q = 0.f;
; #pragma unroll
;     for (int e = 0; e < 32; ++e) { float d = v[e] - mu; q += d * d; }
.Lln1_B1:
	v_mad_i64_i32 v[48:49], s[22:23], v66, s16, v[36:37]
	v_lshl_add_u64 v[60:61], v[48:49], 0, v[38:39]
	v_lshl_add_u64 v[62:63], v[48:49], 0, v[40:41]
	v_lshl_add_u64 v[64:65], v[48:49], 0, v[42:43]
	global_load_dwordx4 v[52:55], v[60:61], off offset:16
	global_load_dwordx4 v[56:59], v[60:61], off
	global_load_dwordx4 v[76:79], v[60:61], off offset:2064
	global_load_dwordx4 v[80:83], v[60:61], off offset:2048
	global_load_dwordx4 v[84:87], v[62:63], off offset:16
	global_load_dwordx4 v[88:91], v[62:63], off
	global_load_dwordx4 v[92:95], v[64:65], off offset:16
	global_load_dwordx4 v[96:99], v[64:65], off
	v_cmp_gt_i32_e32 vcc, s14, v66
	v_mad_i64_i32 v[46:47], s[22:23], v66, s16, v[44:45]
	s_nop 0
	v_cndmask_b32_e32 v16, v73, v74, vcc
	v_lshl_add_u64 v[48:49], s[4:5], 0, v[16:17]
	v_lshl_add_u64 v[60:61], v[48:49], 0, v[38:39]
	v_add_co_u32_e32 v100, vcc, s19, v60
	v_lshl_add_u64 v[50:51], v[46:47], 0, v[38:39]
	s_nop 0
	v_addc_co_u32_e32 v101, vcc, 0, v61, vcc
	v_add_co_u32_e32 v102, vcc, s20, v60
	v_lshl_add_u64 v[62:63], v[60:61], 0, s[6:7]
	s_nop 0
	v_addc_co_u32_e32 v103, vcc, 0, v61, vcc
	v_lshl_add_u64 v[64:65], v[60:61], 0, s[8:9]
	s_waitcnt vmcnt(6)
	s_nop 1
	v_mov_b32_e32 v0, v136
	v_mov_b32_e32 v1, v137
	v_mov_b32_e32 v2, v138
	v_mov_b32_e32 v3, v139
	v_mov_b32_e32 v4, v140
	v_mov_b32_e32 v5, v141
	v_mov_b32_e32 v6, v142
	v_mov_b32_e32 v7, v143
	v_mov_b32_e32 v8, v144
	v_mov_b32_e32 v9, v145
	v_mov_b32_e32 v10, v146
	v_mov_b32_e32 v11, v147
	v_mov_b32_e32 v12, v148
	v_mov_b32_e32 v13, v149
	v_mov_b32_e32 v14, v150
	v_mov_b32_e32 v15, v151
	v_add_f32_e32 v16, v56, v52
	v_add_f32_e32 v108, v57, v53
	v_add_f32_e32 v16, 0, v16
	v_add_f32_e32 v109, v58, v54
	v_add_f32_e32 v16, v108, v16
	v_add_f32_e32 v110, v59, v55
	v_add_f32_e32 v16, v109, v16
	s_waitcnt vmcnt(4)
	v_add_f32_e32 v111, v80, v76
	v_add_f32_e32 v16, v110, v16
	v_add_f32_e32 v112, v81, v77
	v_add_f32_e32 v16, v111, v16
	v_add_f32_e32 v113, v82, v78
	v_add_f32_e32 v16, v112, v16
	v_add_f32_e32 v114, v83, v79
	v_add_f32_e32 v16, v113, v16
	s_waitcnt vmcnt(2)
	v_add_f32_e32 v115, v88, v84
	v_add_f32_e32 v16, v114, v16
	v_add_f32_e32 v116, v89, v85
	v_add_f32_e32 v16, v115, v16
	v_add_f32_e32 v117, v90, v86
	v_add_f32_e32 v16, v116, v16
	v_add_f32_e32 v118, v91, v87
	v_add_f32_e32 v16, v117, v16
	s_waitcnt vmcnt(0)
	v_pk_add_f32 v[104:105], v[96:97], v[92:93]
	v_add_f32_e32 v16, v118, v16
	v_add_f32_e32 v16, v104, v16
	v_pk_add_f32 v[106:107], v[98:99], v[94:95]
	v_add_f32_e32 v16, v105, v16
	v_add_f32_e32 v16, v106, v16
	v_add_f32_e32 v16, v107, v16
	ds_bpermute_b32 v104, v67, v16
	s_waitcnt lgkmcnt(0)
	v_add_f32_e32 v16, v16, v104
	ds_bpermute_b32 v104, v68, v16
	s_waitcnt lgkmcnt(0)
	v_add_f32_e32 v16, v16, v104
	ds_bpermute_b32 v104, v69, v16
	s_waitcnt lgkmcnt(0)
	v_add_f32_e32 v16, v16, v104
	ds_bpermute_b32 v104, v70, v16
	s_waitcnt lgkmcnt(0)
	v_add_f32_e32 v16, v16, v104
	ds_bpermute_b32 v104, v71, v16
	s_waitcnt lgkmcnt(0)
	v_add_f32_e32 v16, v16, v104
	ds_bpermute_b32 v104, v72, v16
	s_waitcnt lgkmcnt(0)
	v_add_f32_e32 v16, v16, v104
	v_mul_f32_e32 v16, 0x3a000000, v16
	v_pk_add_f32 v[108:109], v[56:57], v[16:17] op_sel_hi:[1,0] neg_lo:[0,1] neg_hi:[0,1]
	v_pk_add_f32 v[110:111], v[58:59], v[16:17] op_sel_hi:[1,0] neg_lo:[0,1] neg_hi:[0,1]
	v_pk_add_f32 v[116:117], v[80:81], v[16:17] op_sel_hi:[1,0] neg_lo:[0,1] neg_hi:[0,1]
	v_pk_mul_f32 v[80:81], v[108:109], v[108:109]
	v_pk_add_f32 v[104:105], v[52:53], v[16:17] op_sel_hi:[1,0] neg_lo:[0,1] neg_hi:[0,1]
	v_pk_add_f32 v[106:107], v[54:55], v[16:17] op_sel_hi:[1,0] neg_lo:[0,1] neg_hi:[0,1]
	v_pk_add_f32 v[112:113], v[76:77], v[16:17] op_sel_hi:[1,0] neg_lo:[0,1] neg_hi:[0,1]
	v_pk_add_f32 v[114:115], v[78:79], v[16:17] op_sel_hi:[1,0] neg_lo:[0,1] neg_hi:[0,1]
	v_pk_add_f32 v[118:119], v[82:83], v[16:17] op_sel_hi:[1,0] neg_lo:[0,1] neg_hi:[0,1]
	v_pk_add_f32 v[120:121], v[84:85], v[16:17] op_sel_hi:[1,0] neg_lo:[0,1] neg_hi:[0,1]
	v_pk_add_f32 v[122:123], v[86:87], v[16:17] op_sel_hi:[1,0] neg_lo:[0,1] neg_hi:[0,1]
	v_pk_add_f32 v[88:89], v[88:89], v[16:17] op_sel_hi:[1,0] neg_lo:[0,1] neg_hi:[0,1]
	v_pk_add_f32 v[90:91], v[90:91], v[16:17] op_sel_hi:[1,0] neg_lo:[0,1] neg_hi:[0,1]
	v_pk_add_f32 v[52:53], v[92:93], v[16:17] op_sel_hi:[1,0] neg_lo:[0,1] neg_hi:[0,1]
	v_pk_add_f32 v[54:55], v[94:95], v[16:17] op_sel_hi:[1,0] neg_lo:[0,1] neg_hi:[0,1]
	v_pk_add_f32 v[56:57], v[96:97], v[16:17] op_sel_hi:[1,0] neg_lo:[0,1] neg_hi:[0,1]
	v_pk_add_f32 v[58:59], v[98:99], v[16:17] op_sel_hi:[1,0] neg_lo:[0,1] neg_hi:[0,1]
	v_pk_mul_f32 v[82:83], v[110:111], v[110:111]
	v_add_f32_e32 v16, v80, v81
	v_add_f32_e32 v16, v82, v16
	v_pk_mul_f32 v[76:77], v[104:105], v[104:105]
	v_add_f32_e32 v16, v83, v16
	v_add_f32_e32 v16, v76, v16
	v_pk_mul_f32 v[78:79], v[106:107], v[106:107]
	v_add_f32_e32 v16, v77, v16
	v_add_f32_e32 v16, v78, v16
	v_pk_mul_f32 v[92:93], v[116:117], v[116:117]
	v_add_f32_e32 v16, v79, v16
	v_add_f32_e32 v16, v92, v16
	v_pk_mul_f32 v[94:95], v[118:119], v[118:119]
	v_add_f32_e32 v16, v93, v16
	v_add_f32_e32 v16, v94, v16
	v_pk_mul_f32 v[84:85], v[112:113], v[112:113]
	v_add_f32_e32 v16, v95, v16
	v_add_f32_e32 v16, v84, v16
	v_pk_mul_f32 v[86:87], v[114:115], v[114:115]
	v_add_f32_e32 v16, v85, v16
	v_add_f32_e32 v16, v86, v16
	v_pk_mul_f32 v[124:125], v[88:89], v[88:89]
	v_add_f32_e32 v16, v87, v16
	v_add_f32_e32 v16, v124, v16
	v_pk_mul_f32 v[126:127], v[90:91], v[90:91]
	v_add_f32_e32 v16, v125, v16
	v_add_f32_e32 v16, v126, v16
	v_pk_mul_f32 v[96:97], v[120:121], v[120:121]
	v_add_f32_e32 v16, v127, v16
	v_add_f32_e32 v16, v96, v16
	v_pk_mul_f32 v[98:99], v[122:123], v[122:123]
	v_add_f32_e32 v16, v97, v16
	v_add_f32_e32 v16, v98, v16
	v_pk_mul_f32 v[132:133], v[56:57], v[56:57]
	v_add_f32_e32 v16, v99, v16
	v_add_f32_e32 v16, v132, v16
	v_pk_mul_f32 v[134:135], v[58:59], v[58:59]
	v_add_f32_e32 v16, v133, v16
	v_add_f32_e32 v16, v134, v16
	v_pk_mul_f32 v[128:129], v[52:53], v[52:53]
	v_add_f32_e32 v16, v135, v16
	v_add_f32_e32 v16, v128, v16
	v_pk_mul_f32 v[130:131], v[54:55], v[54:55]
	v_add_f32_e32 v16, v129, v16
	v_add_f32_e32 v16, v130, v16
	v_add_f32_e32 v16, v131, v16
	ds_bpermute_b32 v76, v67, v16
	s_waitcnt lgkmcnt(0)
; DI unsigned pk2(float a, float b) { f32x2 v = {a, b}; bf2_t r = __builtin_convertvector(v, bf2_t); return __builtin_bit_cast(unsigned, r); }
; __device__ __forceinline__ void phase_ln1(const Params& p, int layer, int row0) {
;     ...
;     const float rstd = rsqrtf(wave_sum(q) * (1.f / 2048.f) + LN_EPS);
; #pragma unroll
;     for (int c = 0; c < 4; ++c) {
;       int col = c * 512 + lane * 8;
;       float y[8];
; #pragma unroll
;       for (int e = 0; e < 8; ++e) y[e] = (v[c * 8 + e] - mu) * rstd * G[col + e] + B[col + e];
;       *(f32x4*)(XR + (size_t)row * LDF + col) = f32x4{y[0], y[1], y[2], y[3]};
;       *(f32x4*)(XR + (size_t)row * LDF + col + 4) = f32x4{y[4], y[5], y[6], y[7]};
;       float z[8];
; #pragma unroll
;       for (int e = 0; e < 8; ++e) z[e] = y[e] * (1.f + md[8192 + col + e]) + md[6144 + col + e];
;       u32x4 o = {pk2(z[0], z[1]), pk2(z[2], z[3]), pk2(z[4], z[5]), pk2(z[6], z[7])};
;       *(u32x4*)(XM + (size_t)row * LDX + col) = o;
	v_add_f32_e32 v16, v16, v76
	ds_bpermute_b32 v76, v68, v16
	s_waitcnt lgkmcnt(0)
	v_add_f32_e32 v16, v16, v76
	ds_bpermute_b32 v76, v69, v16
	s_waitcnt lgkmcnt(0)
	v_add_f32_e32 v16, v16, v76
	ds_bpermute_b32 v76, v70, v16
	s_waitcnt lgkmcnt(0)
	v_add_f32_e32 v16, v16, v76
	ds_bpermute_b32 v76, v71, v16
	s_waitcnt lgkmcnt(0)
	v_add_f32_e32 v16, v16, v76
	ds_bpermute_b32 v76, v72, v16
	s_waitcnt lgkmcnt(0)
	v_add_f32_e32 v16, v16, v76
	v_fmamk_f32 v16, v16, 0x3a000000, v75
	v_mul_f32_e32 v76, 0x4b800000, v16
	v_cmp_gt_f32_e32 vcc, s18, v16
	s_nop 1
	v_cndmask_b32_e32 v16, v16, v76, vcc
	v_rsq_f32_e32 v16, v16
	s_nop 0
	v_mul_f32_e32 v76, 0x45800000, v16
	v_cndmask_b32_e32 v16, v16, v76, vcc
	v_pk_mul_f32 v[76:77], v[108:109], v[16:17] op_sel_hi:[1,0]
	v_pk_mul_f32 v[78:79], v[110:111], v[16:17] op_sel_hi:[1,0]
	v_pk_mul_f32 v[80:81], v[104:105], v[16:17] op_sel_hi:[1,0]
	v_pk_mul_f32 v[82:83], v[106:107], v[16:17] op_sel_hi:[1,0]
	v_pk_fma_f32 v[4:5], v[4:5], v[76:77], v[12:13]
	v_pk_fma_f32 v[6:7], v[6:7], v[78:79], v[14:15]
	v_pk_fma_f32 v[8:9], v[0:1], v[80:81], v[8:9]
	v_pk_fma_f32 v[10:11], v[2:3], v[82:83], v[10:11]
	global_store_dwordx4 v[50:51], v[4:7], off
	global_store_dwordx4 v[50:51], v[8:11], off offset:16
	v_mad_i64_i32 v[0:1], s[22:23], v66, s17, v[34:35]
	v_add_u32_e32 v66, s15, v66
	s_nop 1
	v_mov_b32_e32 v12, v152
	v_mov_b32_e32 v13, v153
	v_mov_b32_e32 v14, v154
	v_mov_b32_e32 v15, v155
	v_pk_add_f32 v[2:3], v[12:13], 1.0 op_sel_hi:[1,0]
	v_pk_add_f32 v[12:13], v[14:15], 1.0 op_sel_hi:[1,0]
	s_nop 1
	v_mov_b32_e32 v76, v156
	v_mov_b32_e32 v77, v157
	v_mov_b32_e32 v78, v158
	v_mov_b32_e32 v79, v159
	v_pk_add_f32 v[14:15], v[76:77], 1.0 op_sel_hi:[1,0]
	v_pk_add_f32 v[62:63], v[78:79], 1.0 op_sel_hi:[1,0]
	s_nop 1
	v_mov_b32_e32 v80, v160
	v_mov_b32_e32 v81, v161
	v_mov_b32_e32 v82, v162
	v_mov_b32_e32 v83, v163
	v_pk_fma_f32 v[2:3], v[2:3], v[4:5], v[80:81]
	v_pk_fma_f32 v[4:5], v[12:13], v[6:7], v[82:83]
	s_nop 1
	v_mov_b32_e32 v84, v164
	v_mov_b32_e32 v85, v165
	v_mov_b32_e32 v86, v166
	v_mov_b32_e32 v87, v167
	v_pk_fma_f32 v[6:7], v[14:15], v[8:9], v[84:85]
	v_pk_fma_f32 v[8:9], v[62:63], v[10:11], v[86:87]
	v_cvt_pk_bf16_f32 v2, v2, v3
	v_cvt_pk_bf16_f32 v3, v4, v5
	v_cvt_pk_bf16_f32 v4, v6, v7
	v_cvt_pk_bf16_f32 v5, v8, v9
	global_store_dwordx4 v[0:1], v[2:5], off
	s_nop 0
	v_lshl_add_u64 v[14:15], v[60:61], 0, s[10:11]
	v_lshl_add_u64 v[84:85], v[60:61], 0, s[12:13]
	v_pk_mul_f32 v[60:61], v[116:117], v[16:17] op_sel_hi:[1,0]
	v_pk_mul_f32 v[76:77], v[118:119], v[16:17] op_sel_hi:[1,0]
	v_pk_mul_f32 v[78:79], v[112:113], v[16:17] op_sel_hi:[1,0]
	v_pk_mul_f32 v[80:81], v[114:115], v[16:17] op_sel_hi:[1,0]
	s_nop 1
	v_mov_b32_e32 v2, v168
	v_mov_b32_e32 v3, v169
	v_mov_b32_e32 v4, v170
	v_mov_b32_e32 v5, v171
	v_mov_b32_e32 v6, v172
	v_mov_b32_e32 v7, v173
	v_mov_b32_e32 v8, v174
	v_mov_b32_e32 v9, v175
	v_pk_fma_f32 v[2:3], v[6:7], v[60:61], v[2:3]
	v_pk_fma_f32 v[4:5], v[8:9], v[76:77], v[4:5]
	s_nop 1
	v_mov_b32_e32 v10, v176
	v_mov_b32_e32 v11, v177
	v_mov_b32_e32 v12, v178
	v_mov_b32_e32 v13, v179
	v_mov_b32_e32 v62, v180
	v_mov_b32_e32 v63, v181
	v_mov_b32_e32 v64, v182
	v_mov_b32_e32 v65, v183
	v_pk_fma_f32 v[6:7], v[10:11], v[78:79], v[62:63]
	v_pk_fma_f32 v[8:9], v[12:13], v[80:81], v[64:65]
	global_store_dwordx4 v[50:51], v[2:5], off offset:2048
	global_store_dwordx4 v[50:51], v[6:9], off offset:2064
	s_nop 1
	v_mov_b32_e32 v10, v184
	v_mov_b32_e32 v11, v185
	v_mov_b32_e32 v12, v186
	v_mov_b32_e32 v13, v187
	v_pk_add_f32 v[10:11], v[10:11], 1.0 op_sel_hi:[1,0]
	v_pk_add_f32 v[12:13], v[12:13], 1.0 op_sel_hi:[1,0]
	s_nop 1
	v_mov_b32_e32 v60, v188
	v_mov_b32_e32 v61, v189
	v_mov_b32_e32 v62, v190
	v_mov_b32_e32 v63, v191
	v_pk_add_f32 v[14:15], v[60:61], 1.0 op_sel_hi:[1,0]
	v_pk_add_f32 v[50:51], v[62:63], 1.0 op_sel_hi:[1,0]
	s_nop 1
	v_mov_b32_e32 v76, v192
	v_mov_b32_e32 v77, v193
	v_mov_b32_e32 v78, v194
	v_mov_b32_e32 v79, v195
	v_pk_fma_f32 v[2:3], v[10:11], v[2:3], v[76:77]
	v_pk_fma_f32 v[4:5], v[4:5], v[12:13], v[78:79]
	s_nop 1
	v_mov_b32_e32 v80, v196
	v_mov_b32_e32 v81, v197
	v_mov_b32_e32 v82, v198
	v_mov_b32_e32 v83, v199
	v_pk_fma_f32 v[6:7], v[6:7], v[14:15], v[80:81]
	v_pk_fma_f32 v[8:9], v[8:9], v[50:51], v[82:83]
	v_cvt_pk_bf16_f32 v2, v2, v3
	v_cvt_pk_bf16_f32 v3, v4, v5
	v_cvt_pk_bf16_f32 v4, v6, v7
	v_cvt_pk_bf16_f32 v5, v8, v9
	global_store_dwordx4 v[0:1], v[2:5], off offset:1024
	s_nop 0
	v_lshl_add_u64 v[50:51], v[48:49], 0, v[40:41]
	v_add_co_u32_e32 v86, vcc, s19, v50
; DI unsigned pk2(float a, float b) { f32x2 v = {a, b}; bf2_t r = __builtin_convertvector(v, bf2_t); return __builtin_bit_cast(unsigned, r); }
; __device__ __forceinline__ void phase_ln1(const Params& p, int layer, int row0) {
;     ...
; #pragma unroll
;     for (int c = 0; c < 4; ++c) {
;       int col = c * 512 + lane * 8;
;       float y[8];
; #pragma unroll
;       for (int e = 0; e < 8; ++e) y[e] = (v[c * 8 + e] - mu) * rstd * G[col + e] + B[col + e];
;       *(f32x4*)(XR + (size_t)row * LDF + col) = f32x4{y[0], y[1], y[2], y[3]};
;       *(f32x4*)(XR + (size_t)row * LDF + col + 4) = f32x4{y[4], y[5], y[6], y[7]};
;       float z[8];
; #pragma unroll
;       for (int e = 0; e < 8; ++e) z[e] = y[e] * (1.f + md[8192 + col + e]) + md[6144 + col + e];
;       u32x4 o = {pk2(z[0], z[1]), pk2(z[2], z[3]), pk2(z[4], z[5]), pk2(z[6], z[7])};
;       *(u32x4*)(XM + (size_t)row * LDX + col) = o;
;     }
	v_pk_mul_f32 v[76:77], v[88:89], v[16:17] op_sel_hi:[1,0]
	v_pk_mul_f32 v[78:79], v[90:91], v[16:17] op_sel_hi:[1,0]
	v_lshl_add_u64 v[14:15], v[46:47], 0, v[40:41]
	v_addc_co_u32_e32 v87, vcc, 0, v51, vcc
	v_pk_mul_f32 v[80:81], v[120:121], v[16:17] op_sel_hi:[1,0]
	v_pk_mul_f32 v[82:83], v[122:123], v[16:17] op_sel_hi:[1,0]
	v_lshl_add_u64 v[64:65], v[50:51], 0, s[6:7]
	v_lshl_add_u64 v[84:85], v[50:51], 0, s[8:9]
	v_add_co_u32_e32 v50, vcc, s20, v50
	s_nop 1
	v_mov_b32_e32 v2, v200
	v_mov_b32_e32 v3, v201
	v_mov_b32_e32 v4, v202
	v_mov_b32_e32 v5, v203
	v_mov_b32_e32 v6, v204
	v_mov_b32_e32 v7, v205
	v_mov_b32_e32 v8, v206
	v_mov_b32_e32 v9, v207
	v_pk_fma_f32 v[2:3], v[76:77], v[6:7], v[2:3]
	v_pk_fma_f32 v[4:5], v[78:79], v[8:9], v[4:5]
	s_nop 1
	v_mov_b32_e32 v10, v208
	v_mov_b32_e32 v11, v209
	v_mov_b32_e32 v12, v210
	v_mov_b32_e32 v13, v212
	v_mov_b32_e32 v60, v213
	v_mov_b32_e32 v61, v215
	v_mov_b32_e32 v62, v216
	v_mov_b32_e32 v63, v217
	v_pk_fma_f32 v[6:7], v[80:81], v[10:11], v[60:61]
	v_pk_fma_f32 v[8:9], v[82:83], v[12:13], v[62:63]
	global_store_dwordx4 v[14:15], v[2:5], off
	global_store_dwordx4 v[14:15], v[6:9], off offset:16
	v_addc_co_u32_e32 v51, vcc, 0, v51, vcc
	s_nop 1
	v_mov_b32_e32 v10, v218
	v_mov_b32_e32 v11, v219
	v_mov_b32_e32 v12, v220
	v_mov_b32_e32 v13, v221
	v_pk_add_f32 v[10:11], v[10:11], 1.0 op_sel_hi:[1,0]
	v_pk_add_f32 v[12:13], v[12:13], 1.0 op_sel_hi:[1,0]
	s_nop 1
	v_mov_b32_e32 v60, v222
	v_mov_b32_e32 v61, v223
	v_mov_b32_e32 v62, v224
	v_mov_b32_e32 v63, v225
	v_pk_add_f32 v[14:15], v[60:61], 1.0 op_sel_hi:[1,0]
	v_pk_add_f32 v[50:51], v[62:63], 1.0 op_sel_hi:[1,0]
	s_nop 1
	v_mov_b32_e32 v76, v226
	v_mov_b32_e32 v77, v227
	v_mov_b32_e32 v78, v228
	v_mov_b32_e32 v79, v229
	v_pk_fma_f32 v[2:3], v[2:3], v[10:11], v[76:77]
	v_pk_fma_f32 v[4:5], v[4:5], v[12:13], v[78:79]
	s_nop 1
	v_mov_b32_e32 v80, v230
	v_mov_b32_e32 v81, v231
	v_mov_b32_e32 v82, v232
	v_mov_b32_e32 v83, v233
	v_pk_fma_f32 v[6:7], v[6:7], v[14:15], v[80:81]
	v_pk_fma_f32 v[8:9], v[8:9], v[50:51], v[82:83]
	v_cvt_pk_bf16_f32 v2, v2, v3
	v_cvt_pk_bf16_f32 v3, v4, v5
	v_cvt_pk_bf16_f32 v4, v6, v7
	v_cvt_pk_bf16_f32 v5, v8, v9
	global_store_dwordx4 v[0:1], v[2:5], off offset:2048
	s_nop 0
	v_lshl_add_u64 v[14:15], v[46:47], 0, v[42:43]
	v_lshl_add_u64 v[46:47], v[48:49], 0, v[42:43]
	v_add_co_u32_e32 v78, vcc, s19, v46
	v_lshl_add_u64 v[64:65], v[46:47], 0, s[6:7]
	s_nop 0
	v_addc_co_u32_e32 v79, vcc, 0, v47, vcc
	v_add_co_u32_e32 v80, vcc, s20, v46
	v_lshl_add_u64 v[76:77], v[46:47], 0, s[8:9]
	s_nop 0
	v_addc_co_u32_e32 v81, vcc, 0, v47, vcc
	v_pk_mul_f32 v[46:47], v[56:57], v[16:17] op_sel_hi:[1,0]
	v_pk_mul_f32 v[48:49], v[58:59], v[16:17] op_sel_hi:[1,0]
	v_pk_mul_f32 v[50:51], v[52:53], v[16:17] op_sel_hi:[1,0]
	v_pk_mul_f32 v[52:53], v[54:55], v[16:17] op_sel_hi:[1,0]
	v_cmp_lt_i32_e32 vcc, s21, v66
	s_or_b64 s[0:1], vcc, s[0:1]
	s_nop 1
	v_mov_b32_e32 v2, v234
	v_mov_b32_e32 v3, v235
	v_mov_b32_e32 v4, v236
	v_mov_b32_e32 v5, v237
	v_mov_b32_e32 v6, v238
	v_mov_b32_e32 v7, v240
	v_mov_b32_e32 v8, v241
	v_mov_b32_e32 v9, v242
	v_pk_fma_f32 v[2:3], v[46:47], v[6:7], v[2:3]
	v_pk_fma_f32 v[4:5], v[48:49], v[8:9], v[4:5]
	s_nop 1
	v_mov_b32_e32 v10, v243
	v_mov_b32_e32 v11, v244
	v_mov_b32_e32 v12, v245
	v_mov_b32_e32 v13, v246
	v_mov_b32_e32 v60, v247
	v_mov_b32_e32 v61, v248
	v_mov_b32_e32 v62, v249
	v_mov_b32_e32 v63, v250
	v_pk_fma_f32 v[6:7], v[50:51], v[10:11], v[60:61]
	v_pk_fma_f32 v[8:9], v[52:53], v[12:13], v[62:63]
	global_store_dwordx4 v[14:15], v[2:5], off
	global_store_dwordx4 v[14:15], v[6:9], off offset:16
	global_load_dwordx4 v[10:13], v[78:79], off
	global_load_dwordx4 v[46:49], v[64:65], off offset:16
	global_load_dwordx4 v[50:53], v[80:81], off
	global_load_dwordx4 v[54:57], v[76:77], off offset:16
	s_waitcnt vmcnt(3)
	v_pk_add_f32 v[10:11], v[10:11], 1.0 op_sel_hi:[1,0]
	v_pk_add_f32 v[12:13], v[12:13], 1.0 op_sel_hi:[1,0]
	s_waitcnt vmcnt(2)
	v_pk_add_f32 v[14:15], v[46:47], 1.0 op_sel_hi:[1,0]
	v_pk_add_f32 v[46:47], v[48:49], 1.0 op_sel_hi:[1,0]
	s_waitcnt vmcnt(1)
	v_pk_fma_f32 v[2:3], v[2:3], v[10:11], v[50:51]
	v_pk_fma_f32 v[4:5], v[4:5], v[12:13], v[52:53]
	s_waitcnt vmcnt(0)
	v_pk_fma_f32 v[6:7], v[6:7], v[14:15], v[54:55]
	v_pk_fma_f32 v[8:9], v[8:9], v[46:47], v[56:57]
	v_cvt_pk_bf16_f32 v2, v2, v3
	v_cvt_pk_bf16_f32 v3, v4, v5
	v_cvt_pk_bf16_f32 v4, v6, v7
	v_cvt_pk_bf16_f32 v5, v8, v9
	global_store_dwordx4 v[0:1], v[2:5], off offset:3072
	s_andn2_b64 exec, exec, s[0:1]
	s_cbranch_execnz .Lln1_B1
